# edge work (doc 7.11 style): GEMM K-loop load-phase scalar/address set-up and loop-counter updates hoisted above the preceding barrier
# baseline (speedup 1.0000x reference)
.LBB0_168:
	s_add_u32 s46, s66, 0xfff80080
	s_addc_u32 s47, s67, -1
	s_add_i32 s62, 0, 0x10000
	s_cmp_eq_u32 s82, 28
	s_cselect_b32 s69, s17, s47
	s_cselect_b32 s68, s65, s46
	v_add_u32_e32 v143, s62, v140
	s_cselect_b32 s61, s13, s81
	s_cselect_b32 s60, s79, s80
	s_add_i32 s63, 0, 0x14000
	ds_read_b128 v[144:147], v143
	ds_read_b128 v[148:151], v143 offset:1024
	ds_read_b128 v[152:155], v143 offset:2048
	ds_read_b128 v[156:159], v143 offset:3072
	v_add_u32_e32 v143, s63, v140
	ds_read_b128 v[160:163], v143
	ds_read_b128 v[178:181], v143 offset:1024
	ds_read_b128 v[182:185], v143 offset:2048
	ds_read_b128 v[186:189], v143 offset:3072
	v_lshl_add_u64 v[164:165], s[66:67], 0, v[136:137]
	s_add_i32 m0, s19, 0xc000
	ds_read_b128 v[206:209], v142
	ds_read_b128 v[210:213], v142 offset:1024
	ds_read_b128 v[214:217], v142 offset:2048
	ds_read_b128 v[218:221], v142 offset:3072
	ds_read_b128 v[222:225], v142 offset:4096
	ds_read_b128 v[226:229], v142 offset:5120
	ds_read_b128 v[230:233], v142 offset:6144
	ds_read_b128 v[234:237], v142 offset:7168
	global_load_lds_dwordx4 v[164:165], off
	v_lshl_add_u64 v[164:165], s[66:67], 0, v[138:139]
	s_add_i32 m0, s19, 0xe000
	s_nop 0
	global_load_lds_dwordx4 v[164:165], off
	s_waitcnt vmcnt(8)
	s_waitcnt lgkmcnt(0)
	s_setprio 1
	s_waitcnt lgkmcnt(0)
	v_mfma_f32_16x16x32_bf16 v[126:129], v[144:147], v[206:209], v[126:129]
	v_mfma_f32_16x16x32_bf16 v[122:125], v[152:155], v[206:209], v[122:125]
	v_mfma_f32_16x16x32_bf16 v[118:121], v[144:147], v[214:217], v[118:121]
	v_mfma_f32_16x16x32_bf16 v[114:117], v[152:155], v[214:217], v[114:117]
	s_barrier
	v_mfma_f32_16x16x32_bf16 v[102:105], v[144:147], v[222:225], v[102:105]
	v_mfma_f32_16x16x32_bf16 v[98:101], v[152:155], v[222:225], v[98:101]
	v_mfma_f32_16x16x32_bf16 v[86:89], v[144:147], v[230:233], v[86:89]
	v_mfma_f32_16x16x32_bf16 v[82:85], v[152:155], v[230:233], v[82:85]
	v_mfma_f32_16x16x32_bf16 v[126:129], v[148:151], v[210:213], v[126:129]
	v_mfma_f32_16x16x32_bf16 v[122:125], v[156:159], v[210:213], v[122:125]
	v_mfma_f32_16x16x32_bf16 v[118:121], v[148:151], v[218:221], v[118:121]
	v_mfma_f32_16x16x32_bf16 v[114:117], v[156:159], v[218:221], v[114:117]
	v_mfma_f32_16x16x32_bf16 v[102:105], v[148:151], v[226:229], v[102:105]
	v_mfma_f32_16x16x32_bf16 v[98:101], v[156:159], v[226:229], v[98:101]
	v_mfma_f32_16x16x32_bf16 v[86:89], v[148:151], v[234:237], v[86:89]
	v_mfma_f32_16x16x32_bf16 v[82:85], v[156:159], v[234:237], v[82:85]
	s_setprio 0
	s_setprio 1
	v_mfma_f32_16x16x32_bf16 v[110:113], v[160:163], v[206:209], v[110:113]
	v_mfma_f32_16x16x32_bf16 v[106:109], v[182:185], v[206:209], v[106:109]
	v_mfma_f32_16x16x32_bf16 v[94:97], v[160:163], v[214:217], v[94:97]
	v_mfma_f32_16x16x32_bf16 v[90:93], v[182:185], v[214:217], v[90:93]
	v_mfma_f32_16x16x32_bf16 v[78:81], v[160:163], v[222:225], v[78:81]
	v_mfma_f32_16x16x32_bf16 v[74:77], v[182:185], v[222:225], v[74:77]
	v_mfma_f32_16x16x32_bf16 v[70:73], v[160:163], v[230:233], v[70:73]
	v_mfma_f32_16x16x32_bf16 v[66:69], v[182:185], v[230:233], v[66:69]
	v_mfma_f32_16x16x32_bf16 v[110:113], v[178:181], v[210:213], v[110:113]
	v_mfma_f32_16x16x32_bf16 v[106:109], v[186:189], v[210:213], v[106:109]
	v_mfma_f32_16x16x32_bf16 v[94:97], v[178:181], v[218:221], v[94:97]
	v_mfma_f32_16x16x32_bf16 v[90:93], v[186:189], v[218:221], v[90:93]
	v_mfma_f32_16x16x32_bf16 v[78:81], v[178:181], v[226:229], v[78:81]
	v_mfma_f32_16x16x32_bf16 v[74:77], v[186:189], v[226:229], v[74:77]
	v_mfma_f32_16x16x32_bf16 v[70:73], v[178:181], v[234:237], v[70:73]
	v_mfma_f32_16x16x32_bf16 v[66:69], v[186:189], v[234:237], v[66:69]
	s_setprio 0
	s_add_i32 s46, s62, s71
	v_lshl_add_u64 v[164:165], s[60:61], 0, v[166:167]
	s_mov_b32 m0, s46
	s_barrier
	ds_read_b128 v[206:209], v142 offset:16384
	ds_read_b128 v[210:213], v142 offset:17408
	ds_read_b128 v[214:217], v142 offset:18432
	ds_read_b128 v[218:221], v142 offset:19456
	ds_read_b128 v[222:225], v142 offset:20480
	ds_read_b128 v[226:229], v142 offset:21504
	ds_read_b128 v[230:233], v142 offset:22528
	ds_read_b128 v[234:237], v142 offset:23552
	global_load_lds_dwordx4 v[164:165], off
	s_add_i32 m0, s46, 0x2000
	s_add_u32 s46, s60, 0x80000
	v_lshl_add_u64 v[242:243], s[60:61], 0, v[130:131]
	s_addc_u32 s47, s61, 0
	s_add_i32 s62, s63, s71
	global_load_lds_dwordx4 v[242:243], off
	v_lshl_add_u64 v[244:245], s[46:47], 0, v[166:167]
	s_mov_b32 m0, s62
	v_lshl_add_u64 v[246:247], s[68:69], 0, v[132:133]
	global_load_lds_dwordx4 v[244:245], off
	v_lshl_add_u64 v[244:245], s[46:47], 0, v[130:131]
	s_add_i32 m0, s62, 0x2000
	s_nop 0
	global_load_lds_dwordx4 v[244:245], off
	v_lshl_add_u64 v[244:245], s[68:69], 0, v[134:135]
	s_mov_b32 m0, s19
	s_nop 0
	global_load_lds_dwordx4 v[244:245], off
	s_mov_b32 m0, s73
	s_nop 0
	global_load_lds_dwordx4 v[246:247], off
	s_waitcnt vmcnt(8)
	s_waitcnt lgkmcnt(0)
	s_setprio 1
	s_waitcnt lgkmcnt(0)
	v_mfma_f32_16x16x32_bf16 v[62:65], v[144:147], v[206:209], v[62:65]
	v_mfma_f32_16x16x32_bf16 v[58:61], v[152:155], v[206:209], v[58:61]
	v_mfma_f32_16x16x32_bf16 v[54:57], v[144:147], v[214:217], v[54:57]
	v_mfma_f32_16x16x32_bf16 v[50:53], v[152:155], v[214:217], v[50:53]
	s_barrier
	v_mfma_f32_16x16x32_bf16 v[38:41], v[144:147], v[222:225], v[38:41]
	v_mfma_f32_16x16x32_bf16 v[34:37], v[152:155], v[222:225], v[34:37]
	v_mfma_f32_16x16x32_bf16 v[22:25], v[144:147], v[230:233], v[22:25]
	v_mfma_f32_16x16x32_bf16 v[18:21], v[152:155], v[230:233], v[18:21]
	v_mfma_f32_16x16x32_bf16 v[62:65], v[148:151], v[210:213], v[62:65]
	v_mfma_f32_16x16x32_bf16 v[58:61], v[156:159], v[210:213], v[58:61]
	v_mfma_f32_16x16x32_bf16 v[54:57], v[148:151], v[218:221], v[54:57]
	v_mfma_f32_16x16x32_bf16 v[50:53], v[156:159], v[218:221], v[50:53]
	v_mfma_f32_16x16x32_bf16 v[38:41], v[148:151], v[226:229], v[38:41]
	v_mfma_f32_16x16x32_bf16 v[34:37], v[156:159], v[226:229], v[34:37]
	v_mfma_f32_16x16x32_bf16 v[22:25], v[148:151], v[234:237], v[22:25]
	v_mfma_f32_16x16x32_bf16 v[18:21], v[156:159], v[234:237], v[18:21]
	s_setprio 0
	s_setprio 1
	v_mfma_f32_16x16x32_bf16 v[46:49], v[160:163], v[206:209], v[46:49]
	v_mfma_f32_16x16x32_bf16 v[42:45], v[182:185], v[206:209], v[42:45]
	v_mfma_f32_16x16x32_bf16 v[30:33], v[160:163], v[214:217], v[30:33]
	v_mfma_f32_16x16x32_bf16 v[26:29], v[182:185], v[214:217], v[26:29]
	v_mfma_f32_16x16x32_bf16 v[14:17], v[160:163], v[222:225], v[14:17]
	v_mfma_f32_16x16x32_bf16 v[10:13], v[182:185], v[222:225], v[10:13]
	v_mfma_f32_16x16x32_bf16 v[6:9], v[160:163], v[230:233], v[6:9]
	v_mfma_f32_16x16x32_bf16 v[2:5], v[182:185], v[230:233], v[2:5]
	v_mfma_f32_16x16x32_bf16 v[46:49], v[178:181], v[210:213], v[46:49]
	v_mfma_f32_16x16x32_bf16 v[42:45], v[186:189], v[210:213], v[42:45]
	v_mfma_f32_16x16x32_bf16 v[30:33], v[178:181], v[218:221], v[30:33]
	v_mfma_f32_16x16x32_bf16 v[26:29], v[186:189], v[218:221], v[26:29]
	v_mfma_f32_16x16x32_bf16 v[14:17], v[178:181], v[226:229], v[14:17]
	v_mfma_f32_16x16x32_bf16 v[10:13], v[186:189], v[226:229], v[10:13]
	v_mfma_f32_16x16x32_bf16 v[6:9], v[178:181], v[234:237], v[6:9]
	v_mfma_f32_16x16x32_bf16 v[2:5], v[186:189], v[234:237], v[2:5]
	s_setprio 0
	s_add_i32 s62, 0, 0x18000
	v_add_u32_e32 v143, s62, v140
	s_add_i32 s63, 0, 0x1c000
	s_barrier
	ds_read_b128 v[144:147], v143
	ds_read_b128 v[148:151], v143 offset:1024
	ds_read_b128 v[152:155], v143 offset:2048
	ds_read_b128 v[156:159], v143 offset:3072
	v_add_u32_e32 v143, s63, v140
	ds_read_b128 v[160:163], v143
	ds_read_b128 v[178:181], v143 offset:1024
	ds_read_b128 v[182:185], v143 offset:2048
	ds_read_b128 v[186:189], v143 offset:3072
	s_add_u32 s46, s68, 0x80000
	s_addc_u32 s47, s69, 0
	s_mov_b32 m0, s74
	v_lshl_add_u64 v[248:249], s[46:47], 0, v[134:135]
	ds_read_b128 v[206:209], v142 offset:32768
	ds_read_b128 v[210:213], v142 offset:33792
	ds_read_b128 v[214:217], v142 offset:34816
	ds_read_b128 v[218:221], v142 offset:35840
	ds_read_b128 v[222:225], v142 offset:36864
	ds_read_b128 v[226:229], v142 offset:37888
	ds_read_b128 v[230:233], v142 offset:38912
	ds_read_b128 v[234:237], v142 offset:39936
	global_load_lds_dwordx4 v[248:249], off
	v_lshl_add_u64 v[248:249], s[46:47], 0, v[132:133]
	s_mov_b32 m0, s75
	s_nop 0
	global_load_lds_dwordx4 v[248:249], off
	s_waitcnt vmcnt(8)
	s_waitcnt lgkmcnt(0)
	s_setprio 1
	s_waitcnt lgkmcnt(0)
	v_mfma_f32_16x16x32_bf16 v[126:129], v[144:147], v[206:209], v[126:129]
	v_mfma_f32_16x16x32_bf16 v[122:125], v[152:155], v[206:209], v[122:125]
	v_mfma_f32_16x16x32_bf16 v[118:121], v[144:147], v[214:217], v[118:121]
	v_mfma_f32_16x16x32_bf16 v[114:117], v[152:155], v[214:217], v[114:117]
	s_barrier
	v_mfma_f32_16x16x32_bf16 v[102:105], v[144:147], v[222:225], v[102:105]
	v_mfma_f32_16x16x32_bf16 v[98:101], v[152:155], v[222:225], v[98:101]
	v_mfma_f32_16x16x32_bf16 v[86:89], v[144:147], v[230:233], v[86:89]
	v_mfma_f32_16x16x32_bf16 v[82:85], v[152:155], v[230:233], v[82:85]
	v_mfma_f32_16x16x32_bf16 v[126:129], v[148:151], v[210:213], v[126:129]
	v_mfma_f32_16x16x32_bf16 v[122:125], v[156:159], v[210:213], v[122:125]
	v_mfma_f32_16x16x32_bf16 v[118:121], v[148:151], v[218:221], v[118:121]
	v_mfma_f32_16x16x32_bf16 v[114:117], v[156:159], v[218:221], v[114:117]
	v_mfma_f32_16x16x32_bf16 v[102:105], v[148:151], v[226:229], v[102:105]
	v_mfma_f32_16x16x32_bf16 v[98:101], v[156:159], v[226:229], v[98:101]
	v_mfma_f32_16x16x32_bf16 v[86:89], v[148:151], v[234:237], v[86:89]
	v_mfma_f32_16x16x32_bf16 v[82:85], v[156:159], v[234:237], v[82:85]
	s_setprio 0
	s_setprio 1
	v_mfma_f32_16x16x32_bf16 v[110:113], v[160:163], v[206:209], v[110:113]
	v_mfma_f32_16x16x32_bf16 v[106:109], v[182:185], v[206:209], v[106:109]
	v_mfma_f32_16x16x32_bf16 v[94:97], v[160:163], v[214:217], v[94:97]
	v_mfma_f32_16x16x32_bf16 v[90:93], v[182:185], v[214:217], v[90:93]
	v_mfma_f32_16x16x32_bf16 v[78:81], v[160:163], v[222:225], v[78:81]
	v_mfma_f32_16x16x32_bf16 v[74:77], v[182:185], v[222:225], v[74:77]
	v_mfma_f32_16x16x32_bf16 v[70:73], v[160:163], v[230:233], v[70:73]
	v_mfma_f32_16x16x32_bf16 v[66:69], v[182:185], v[230:233], v[66:69]
	v_mfma_f32_16x16x32_bf16 v[110:113], v[178:181], v[210:213], v[110:113]
	v_mfma_f32_16x16x32_bf16 v[106:109], v[186:189], v[210:213], v[106:109]
	v_mfma_f32_16x16x32_bf16 v[94:97], v[178:181], v[218:221], v[94:97]
	v_mfma_f32_16x16x32_bf16 v[90:93], v[186:189], v[218:221], v[90:93]
	v_mfma_f32_16x16x32_bf16 v[78:81], v[178:181], v[226:229], v[78:81]
	v_mfma_f32_16x16x32_bf16 v[74:77], v[186:189], v[226:229], v[74:77]
	v_mfma_f32_16x16x32_bf16 v[70:73], v[178:181], v[234:237], v[70:73]
	v_mfma_f32_16x16x32_bf16 v[66:69], v[186:189], v[234:237], v[66:69]
	s_setprio 0
	s_add_i32 s46, s62, s71
	v_lshl_add_u64 v[164:165], v[164:165], 0, s[42:43]
	s_mov_b32 m0, s46
	s_barrier
	ds_read_b128 v[206:209], v142 offset:49152
	ds_read_b128 v[210:213], v142 offset:50176
	ds_read_b128 v[214:217], v142 offset:51200
	ds_read_b128 v[218:221], v142 offset:52224
	ds_read_b128 v[222:225], v142 offset:53248
	ds_read_b128 v[226:229], v142 offset:54272
	ds_read_b128 v[230:233], v142 offset:55296
	ds_read_b128 v[234:237], v142 offset:56320
	global_load_lds_dwordx4 v[164:165], off
	s_add_i32 m0, s46, 0x2000
	s_add_u32 s46, s60, 0x80080
	v_lshl_add_u64 v[164:165], v[242:243], 0, s[42:43]
	s_addc_u32 s47, s61, 0
	s_add_i32 s60, s63, s71
	global_load_lds_dwordx4 v[164:165], off
	v_lshl_add_u64 v[164:165], s[46:47], 0, v[166:167]
	s_mov_b32 m0, s60
	s_nop 0
	global_load_lds_dwordx4 v[164:165], off
	v_lshl_add_u64 v[164:165], s[46:47], 0, v[130:131]
	s_add_i32 m0, s60, 0x2000
	s_nop 0
	global_load_lds_dwordx4 v[164:165], off
	v_lshl_add_u64 v[164:165], v[244:245], 0, s[42:43]
	s_mov_b32 m0, s76
	s_nop 0
	global_load_lds_dwordx4 v[164:165], off
	v_lshl_add_u64 v[164:165], v[246:247], 0, s[42:43]
	s_mov_b32 m0, s77
	s_nop 0
	global_load_lds_dwordx4 v[164:165], off
	s_waitcnt vmcnt(8)
	s_waitcnt lgkmcnt(0)
	s_setprio 1
	s_waitcnt lgkmcnt(0)
	v_mfma_f32_16x16x32_bf16 v[62:65], v[144:147], v[206:209], v[62:65]
	v_mfma_f32_16x16x32_bf16 v[58:61], v[152:155], v[206:209], v[58:61]
	v_mfma_f32_16x16x32_bf16 v[54:57], v[144:147], v[214:217], v[54:57]
	v_mfma_f32_16x16x32_bf16 v[50:53], v[152:155], v[214:217], v[50:53]
	s_barrier
	v_mfma_f32_16x16x32_bf16 v[38:41], v[144:147], v[222:225], v[38:41]
	v_mfma_f32_16x16x32_bf16 v[34:37], v[152:155], v[222:225], v[34:37]
	v_mfma_f32_16x16x32_bf16 v[22:25], v[144:147], v[230:233], v[22:25]
	v_mfma_f32_16x16x32_bf16 v[18:21], v[152:155], v[230:233], v[18:21]
	v_mfma_f32_16x16x32_bf16 v[62:65], v[148:151], v[210:213], v[62:65]
	v_mfma_f32_16x16x32_bf16 v[58:61], v[156:159], v[210:213], v[58:61]
	v_mfma_f32_16x16x32_bf16 v[54:57], v[148:151], v[218:221], v[54:57]
	v_mfma_f32_16x16x32_bf16 v[50:53], v[156:159], v[218:221], v[50:53]
	v_mfma_f32_16x16x32_bf16 v[38:41], v[148:151], v[226:229], v[38:41]
	v_mfma_f32_16x16x32_bf16 v[34:37], v[156:159], v[226:229], v[34:37]
	v_mfma_f32_16x16x32_bf16 v[22:25], v[148:151], v[234:237], v[22:25]
	v_mfma_f32_16x16x32_bf16 v[18:21], v[156:159], v[234:237], v[18:21]
	s_setprio 0
	s_setprio 1
	v_mfma_f32_16x16x32_bf16 v[46:49], v[160:163], v[206:209], v[46:49]
	v_mfma_f32_16x16x32_bf16 v[42:45], v[182:185], v[206:209], v[42:45]
	v_mfma_f32_16x16x32_bf16 v[30:33], v[160:163], v[214:217], v[30:33]
	v_mfma_f32_16x16x32_bf16 v[26:29], v[182:185], v[214:217], v[26:29]
	v_mfma_f32_16x16x32_bf16 v[14:17], v[160:163], v[222:225], v[14:17]
	v_mfma_f32_16x16x32_bf16 v[10:13], v[182:185], v[222:225], v[10:13]
	v_mfma_f32_16x16x32_bf16 v[6:9], v[160:163], v[230:233], v[6:9]
	v_mfma_f32_16x16x32_bf16 v[2:5], v[182:185], v[230:233], v[2:5]
	v_mfma_f32_16x16x32_bf16 v[46:49], v[178:181], v[210:213], v[46:49]
	v_mfma_f32_16x16x32_bf16 v[42:45], v[186:189], v[210:213], v[42:45]
	v_mfma_f32_16x16x32_bf16 v[30:33], v[178:181], v[218:221], v[30:33]
	v_mfma_f32_16x16x32_bf16 v[26:29], v[186:189], v[218:221], v[26:29]
	v_mfma_f32_16x16x32_bf16 v[14:17], v[178:181], v[226:229], v[14:17]
	v_mfma_f32_16x16x32_bf16 v[10:13], v[186:189], v[226:229], v[10:13]
	v_mfma_f32_16x16x32_bf16 v[6:9], v[178:181], v[234:237], v[6:9]
	v_mfma_f32_16x16x32_bf16 v[2:5], v[186:189], v[234:237], v[2:5]
	s_setprio 0
	s_add_i32 s82, s82, 2
	s_add_u32 s66, s66, 0x100
	s_addc_u32 s67, s67, 0
	s_add_u32 s80, s80, 0x100
	s_addc_u32 s81, s81, 0
	s_cmp_gt_u32 s82, 29
	s_barrier
	s_cbranch_scc0 .LBB0_168
	s_and_b64 vcc, exec, s[10:11]
	s_cbranch_vccz .LBB0_171
	s_barrier

.LBB0_426:
	s_add_u32 s46, s66, 0xfffe0080
	s_addc_u32 s47, s67, -1
	s_add_i32 s62, 0, 0x10000
	s_cmp_eq_u32 s84, 4
	s_cselect_b32 s69, s19, s47
	s_cselect_b32 s68, s80, s46
	v_add_u32_e32 v143, s62, v140
	s_cselect_b32 s61, s17, s83
	s_cselect_b32 s60, s81, s82
	s_add_i32 s63, 0, 0x14000
	ds_read_b128 v[144:147], v143
	ds_read_b128 v[148:151], v143 offset:1024
	ds_read_b128 v[152:155], v143 offset:2048
	ds_read_b128 v[156:159], v143 offset:3072
	v_add_u32_e32 v143, s63, v140
	ds_read_b128 v[160:163], v143
	ds_read_b128 v[178:181], v143 offset:1024
	ds_read_b128 v[182:185], v143 offset:2048
	ds_read_b128 v[186:189], v143 offset:3072
	v_lshl_add_u64 v[164:165], s[66:67], 0, v[136:137]
	s_add_i32 m0, s11, 0xc000
	ds_read_b128 v[206:209], v142
	ds_read_b128 v[210:213], v142 offset:1024
	ds_read_b128 v[214:217], v142 offset:2048
	ds_read_b128 v[218:221], v142 offset:3072
	ds_read_b128 v[222:225], v142 offset:4096
	ds_read_b128 v[226:229], v142 offset:5120
	ds_read_b128 v[230:233], v142 offset:6144
	ds_read_b128 v[234:237], v142 offset:7168
	global_load_lds_dwordx4 v[164:165], off
	v_lshl_add_u64 v[164:165], s[66:67], 0, v[138:139]
	s_add_i32 m0, s11, 0xe000
	s_nop 0
	global_load_lds_dwordx4 v[164:165], off
	s_waitcnt vmcnt(8)
	s_waitcnt lgkmcnt(0)
	s_setprio 1
	s_waitcnt lgkmcnt(0)
	v_mfma_f32_16x16x32_bf16 v[126:129], v[144:147], v[206:209], v[126:129]
	v_mfma_f32_16x16x32_bf16 v[122:125], v[152:155], v[206:209], v[122:125]
	v_mfma_f32_16x16x32_bf16 v[118:121], v[144:147], v[214:217], v[118:121]
	v_mfma_f32_16x16x32_bf16 v[114:117], v[152:155], v[214:217], v[114:117]
	s_barrier
	v_mfma_f32_16x16x32_bf16 v[102:105], v[144:147], v[222:225], v[102:105]
	v_mfma_f32_16x16x32_bf16 v[98:101], v[152:155], v[222:225], v[98:101]
	v_mfma_f32_16x16x32_bf16 v[86:89], v[144:147], v[230:233], v[86:89]
	v_mfma_f32_16x16x32_bf16 v[82:85], v[152:155], v[230:233], v[82:85]
	v_mfma_f32_16x16x32_bf16 v[126:129], v[148:151], v[210:213], v[126:129]
	v_mfma_f32_16x16x32_bf16 v[122:125], v[156:159], v[210:213], v[122:125]
	v_mfma_f32_16x16x32_bf16 v[118:121], v[148:151], v[218:221], v[118:121]
	v_mfma_f32_16x16x32_bf16 v[114:117], v[156:159], v[218:221], v[114:117]
	v_mfma_f32_16x16x32_bf16 v[102:105], v[148:151], v[226:229], v[102:105]
	v_mfma_f32_16x16x32_bf16 v[98:101], v[156:159], v[226:229], v[98:101]
	v_mfma_f32_16x16x32_bf16 v[86:89], v[148:151], v[234:237], v[86:89]
	v_mfma_f32_16x16x32_bf16 v[82:85], v[156:159], v[234:237], v[82:85]
	s_setprio 0
	s_setprio 1
	v_mfma_f32_16x16x32_bf16 v[110:113], v[160:163], v[206:209], v[110:113]
	v_mfma_f32_16x16x32_bf16 v[106:109], v[182:185], v[206:209], v[106:109]
	v_mfma_f32_16x16x32_bf16 v[94:97], v[160:163], v[214:217], v[94:97]
	v_mfma_f32_16x16x32_bf16 v[90:93], v[182:185], v[214:217], v[90:93]
	v_mfma_f32_16x16x32_bf16 v[78:81], v[160:163], v[222:225], v[78:81]
	v_mfma_f32_16x16x32_bf16 v[74:77], v[182:185], v[222:225], v[74:77]
	v_mfma_f32_16x16x32_bf16 v[70:73], v[160:163], v[230:233], v[70:73]
	v_mfma_f32_16x16x32_bf16 v[66:69], v[182:185], v[230:233], v[66:69]
	v_mfma_f32_16x16x32_bf16 v[110:113], v[178:181], v[210:213], v[110:113]
	v_mfma_f32_16x16x32_bf16 v[106:109], v[186:189], v[210:213], v[106:109]
	v_mfma_f32_16x16x32_bf16 v[94:97], v[178:181], v[218:221], v[94:97]
	v_mfma_f32_16x16x32_bf16 v[90:93], v[186:189], v[218:221], v[90:93]
	v_mfma_f32_16x16x32_bf16 v[78:81], v[178:181], v[226:229], v[78:81]
	v_mfma_f32_16x16x32_bf16 v[74:77], v[186:189], v[226:229], v[74:77]
	v_mfma_f32_16x16x32_bf16 v[70:73], v[178:181], v[234:237], v[70:73]
	v_mfma_f32_16x16x32_bf16 v[66:69], v[186:189], v[234:237], v[66:69]
	s_setprio 0
	s_add_i32 s46, s62, s72
	v_lshl_add_u64 v[164:165], s[60:61], 0, v[166:167]
	s_mov_b32 m0, s46
	s_barrier
	ds_read_b128 v[206:209], v142 offset:16384
	ds_read_b128 v[210:213], v142 offset:17408
	ds_read_b128 v[214:217], v142 offset:18432
	ds_read_b128 v[218:221], v142 offset:19456
	ds_read_b128 v[222:225], v142 offset:20480
	ds_read_b128 v[226:229], v142 offset:21504
	ds_read_b128 v[230:233], v142 offset:22528
	ds_read_b128 v[234:237], v142 offset:23552
	global_load_lds_dwordx4 v[164:165], off
	s_add_i32 m0, s46, 0x2000
	s_add_u32 s46, s60, 0x20000
	v_lshl_add_u64 v[242:243], s[60:61], 0, v[130:131]
	s_addc_u32 s47, s61, 0
	s_add_i32 s62, s63, s72
	global_load_lds_dwordx4 v[242:243], off
	v_lshl_add_u64 v[244:245], s[46:47], 0, v[166:167]
	s_mov_b32 m0, s62
	v_lshl_add_u64 v[246:247], s[68:69], 0, v[132:133]
	global_load_lds_dwordx4 v[244:245], off
	v_lshl_add_u64 v[244:245], s[46:47], 0, v[130:131]
	s_add_i32 m0, s62, 0x2000
	s_nop 0
	global_load_lds_dwordx4 v[244:245], off
	v_lshl_add_u64 v[244:245], s[68:69], 0, v[134:135]
	s_mov_b32 m0, s11
	s_nop 0
	global_load_lds_dwordx4 v[244:245], off
	s_mov_b32 m0, s74
	s_nop 0
	global_load_lds_dwordx4 v[246:247], off
	s_waitcnt vmcnt(8)
	s_waitcnt lgkmcnt(0)
	s_setprio 1
	s_waitcnt lgkmcnt(0)
	v_mfma_f32_16x16x32_bf16 v[62:65], v[144:147], v[206:209], v[62:65]
	v_mfma_f32_16x16x32_bf16 v[58:61], v[152:155], v[206:209], v[58:61]
	v_mfma_f32_16x16x32_bf16 v[54:57], v[144:147], v[214:217], v[54:57]
	v_mfma_f32_16x16x32_bf16 v[50:53], v[152:155], v[214:217], v[50:53]
	s_barrier
	v_mfma_f32_16x16x32_bf16 v[38:41], v[144:147], v[222:225], v[38:41]
	v_mfma_f32_16x16x32_bf16 v[34:37], v[152:155], v[222:225], v[34:37]
	v_mfma_f32_16x16x32_bf16 v[22:25], v[144:147], v[230:233], v[22:25]
	v_mfma_f32_16x16x32_bf16 v[18:21], v[152:155], v[230:233], v[18:21]
	v_mfma_f32_16x16x32_bf16 v[62:65], v[148:151], v[210:213], v[62:65]
	v_mfma_f32_16x16x32_bf16 v[58:61], v[156:159], v[210:213], v[58:61]
	v_mfma_f32_16x16x32_bf16 v[54:57], v[148:151], v[218:221], v[54:57]
	v_mfma_f32_16x16x32_bf16 v[50:53], v[156:159], v[218:221], v[50:53]
	v_mfma_f32_16x16x32_bf16 v[38:41], v[148:151], v[226:229], v[38:41]
	v_mfma_f32_16x16x32_bf16 v[34:37], v[156:159], v[226:229], v[34:37]
	v_mfma_f32_16x16x32_bf16 v[22:25], v[148:151], v[234:237], v[22:25]
	v_mfma_f32_16x16x32_bf16 v[18:21], v[156:159], v[234:237], v[18:21]
	s_setprio 0
	s_setprio 1
	v_mfma_f32_16x16x32_bf16 v[46:49], v[160:163], v[206:209], v[46:49]
	v_mfma_f32_16x16x32_bf16 v[42:45], v[182:185], v[206:209], v[42:45]
	v_mfma_f32_16x16x32_bf16 v[30:33], v[160:163], v[214:217], v[30:33]
	v_mfma_f32_16x16x32_bf16 v[26:29], v[182:185], v[214:217], v[26:29]
	v_mfma_f32_16x16x32_bf16 v[14:17], v[160:163], v[222:225], v[14:17]
	v_mfma_f32_16x16x32_bf16 v[10:13], v[182:185], v[222:225], v[10:13]
	v_mfma_f32_16x16x32_bf16 v[6:9], v[160:163], v[230:233], v[6:9]
	v_mfma_f32_16x16x32_bf16 v[2:5], v[182:185], v[230:233], v[2:5]
	v_mfma_f32_16x16x32_bf16 v[46:49], v[178:181], v[210:213], v[46:49]
	v_mfma_f32_16x16x32_bf16 v[42:45], v[186:189], v[210:213], v[42:45]
	v_mfma_f32_16x16x32_bf16 v[30:33], v[178:181], v[218:221], v[30:33]
	v_mfma_f32_16x16x32_bf16 v[26:29], v[186:189], v[218:221], v[26:29]
	v_mfma_f32_16x16x32_bf16 v[14:17], v[178:181], v[226:229], v[14:17]
	v_mfma_f32_16x16x32_bf16 v[10:13], v[186:189], v[226:229], v[10:13]
	v_mfma_f32_16x16x32_bf16 v[6:9], v[178:181], v[234:237], v[6:9]
	v_mfma_f32_16x16x32_bf16 v[2:5], v[186:189], v[234:237], v[2:5]
	s_setprio 0
	s_add_i32 s62, 0, 0x18000
	v_add_u32_e32 v143, s62, v140
	s_add_i32 s63, 0, 0x1c000
	s_barrier
	ds_read_b128 v[144:147], v143
	ds_read_b128 v[148:151], v143 offset:1024
	ds_read_b128 v[152:155], v143 offset:2048
	ds_read_b128 v[156:159], v143 offset:3072
	v_add_u32_e32 v143, s63, v140
	ds_read_b128 v[160:163], v143
	ds_read_b128 v[178:181], v143 offset:1024
	ds_read_b128 v[182:185], v143 offset:2048
	ds_read_b128 v[186:189], v143 offset:3072
	s_add_u32 s46, s68, 0x20000
	s_addc_u32 s47, s69, 0
	s_mov_b32 m0, s75
	v_lshl_add_u64 v[248:249], s[46:47], 0, v[134:135]
	ds_read_b128 v[206:209], v142 offset:32768
	ds_read_b128 v[210:213], v142 offset:33792
	ds_read_b128 v[214:217], v142 offset:34816
	ds_read_b128 v[218:221], v142 offset:35840
	ds_read_b128 v[222:225], v142 offset:36864
	ds_read_b128 v[226:229], v142 offset:37888
	ds_read_b128 v[230:233], v142 offset:38912
	ds_read_b128 v[234:237], v142 offset:39936
	global_load_lds_dwordx4 v[248:249], off
	v_lshl_add_u64 v[248:249], s[46:47], 0, v[132:133]
	s_mov_b32 m0, s76
	s_nop 0
	global_load_lds_dwordx4 v[248:249], off
	s_waitcnt vmcnt(8)
	s_waitcnt lgkmcnt(0)
	s_setprio 1
	s_waitcnt lgkmcnt(0)
	v_mfma_f32_16x16x32_bf16 v[126:129], v[144:147], v[206:209], v[126:129]
	v_mfma_f32_16x16x32_bf16 v[122:125], v[152:155], v[206:209], v[122:125]
	v_mfma_f32_16x16x32_bf16 v[118:121], v[144:147], v[214:217], v[118:121]
	v_mfma_f32_16x16x32_bf16 v[114:117], v[152:155], v[214:217], v[114:117]
	s_barrier
	v_mfma_f32_16x16x32_bf16 v[102:105], v[144:147], v[222:225], v[102:105]
	v_mfma_f32_16x16x32_bf16 v[98:101], v[152:155], v[222:225], v[98:101]
	v_mfma_f32_16x16x32_bf16 v[86:89], v[144:147], v[230:233], v[86:89]
	v_mfma_f32_16x16x32_bf16 v[82:85], v[152:155], v[230:233], v[82:85]
	v_mfma_f32_16x16x32_bf16 v[126:129], v[148:151], v[210:213], v[126:129]
	v_mfma_f32_16x16x32_bf16 v[122:125], v[156:159], v[210:213], v[122:125]
	v_mfma_f32_16x16x32_bf16 v[118:121], v[148:151], v[218:221], v[118:121]
	v_mfma_f32_16x16x32_bf16 v[114:117], v[156:159], v[218:221], v[114:117]
	v_mfma_f32_16x16x32_bf16 v[102:105], v[148:151], v[226:229], v[102:105]
	v_mfma_f32_16x16x32_bf16 v[98:101], v[156:159], v[226:229], v[98:101]
	v_mfma_f32_16x16x32_bf16 v[86:89], v[148:151], v[234:237], v[86:89]
	v_mfma_f32_16x16x32_bf16 v[82:85], v[156:159], v[234:237], v[82:85]
	s_setprio 0
	s_setprio 1
	v_mfma_f32_16x16x32_bf16 v[110:113], v[160:163], v[206:209], v[110:113]
	v_mfma_f32_16x16x32_bf16 v[106:109], v[182:185], v[206:209], v[106:109]
	v_mfma_f32_16x16x32_bf16 v[94:97], v[160:163], v[214:217], v[94:97]
	v_mfma_f32_16x16x32_bf16 v[90:93], v[182:185], v[214:217], v[90:93]
	v_mfma_f32_16x16x32_bf16 v[78:81], v[160:163], v[222:225], v[78:81]
	v_mfma_f32_16x16x32_bf16 v[74:77], v[182:185], v[222:225], v[74:77]
	v_mfma_f32_16x16x32_bf16 v[70:73], v[160:163], v[230:233], v[70:73]
	v_mfma_f32_16x16x32_bf16 v[66:69], v[182:185], v[230:233], v[66:69]
	v_mfma_f32_16x16x32_bf16 v[110:113], v[178:181], v[210:213], v[110:113]
	v_mfma_f32_16x16x32_bf16 v[106:109], v[186:189], v[210:213], v[106:109]
	v_mfma_f32_16x16x32_bf16 v[94:97], v[178:181], v[218:221], v[94:97]
	v_mfma_f32_16x16x32_bf16 v[90:93], v[186:189], v[218:221], v[90:93]
	v_mfma_f32_16x16x32_bf16 v[78:81], v[178:181], v[226:229], v[78:81]
	v_mfma_f32_16x16x32_bf16 v[74:77], v[186:189], v[226:229], v[74:77]
	v_mfma_f32_16x16x32_bf16 v[70:73], v[178:181], v[234:237], v[70:73]
	v_mfma_f32_16x16x32_bf16 v[66:69], v[186:189], v[234:237], v[66:69]
	s_setprio 0
	s_add_i32 s46, s62, s72
	v_lshl_add_u64 v[164:165], v[164:165], 0, s[42:43]
	s_mov_b32 m0, s46
	s_barrier
	ds_read_b128 v[206:209], v142 offset:49152
	ds_read_b128 v[210:213], v142 offset:50176
	ds_read_b128 v[214:217], v142 offset:51200
	ds_read_b128 v[218:221], v142 offset:52224
	ds_read_b128 v[222:225], v142 offset:53248
	ds_read_b128 v[226:229], v142 offset:54272
	ds_read_b128 v[230:233], v142 offset:55296
	ds_read_b128 v[234:237], v142 offset:56320
	global_load_lds_dwordx4 v[164:165], off
	s_add_i32 m0, s46, 0x2000
	s_add_u32 s46, s60, 0x20080
	v_lshl_add_u64 v[164:165], v[242:243], 0, s[42:43]
	s_addc_u32 s47, s61, 0
	s_add_i32 s60, s63, s72
	global_load_lds_dwordx4 v[164:165], off
	v_lshl_add_u64 v[164:165], s[46:47], 0, v[166:167]
	s_mov_b32 m0, s60
	s_nop 0
	global_load_lds_dwordx4 v[164:165], off
	v_lshl_add_u64 v[164:165], s[46:47], 0, v[130:131]
	s_add_i32 m0, s60, 0x2000
	s_nop 0
	global_load_lds_dwordx4 v[164:165], off
	v_lshl_add_u64 v[164:165], v[244:245], 0, s[42:43]
	s_mov_b32 m0, s77
	s_nop 0
	global_load_lds_dwordx4 v[164:165], off
	v_lshl_add_u64 v[164:165], v[246:247], 0, s[42:43]
	s_mov_b32 m0, s78
	s_nop 0
	global_load_lds_dwordx4 v[164:165], off
	s_waitcnt vmcnt(8)
	s_waitcnt lgkmcnt(0)
	s_setprio 1
	s_waitcnt lgkmcnt(0)
	v_mfma_f32_16x16x32_bf16 v[62:65], v[144:147], v[206:209], v[62:65]
	v_mfma_f32_16x16x32_bf16 v[58:61], v[152:155], v[206:209], v[58:61]
	v_mfma_f32_16x16x32_bf16 v[54:57], v[144:147], v[214:217], v[54:57]
	v_mfma_f32_16x16x32_bf16 v[50:53], v[152:155], v[214:217], v[50:53]
	s_barrier
	v_mfma_f32_16x16x32_bf16 v[38:41], v[144:147], v[222:225], v[38:41]
	v_mfma_f32_16x16x32_bf16 v[34:37], v[152:155], v[222:225], v[34:37]
	v_mfma_f32_16x16x32_bf16 v[22:25], v[144:147], v[230:233], v[22:25]
	v_mfma_f32_16x16x32_bf16 v[18:21], v[152:155], v[230:233], v[18:21]
	v_mfma_f32_16x16x32_bf16 v[62:65], v[148:151], v[210:213], v[62:65]
	v_mfma_f32_16x16x32_bf16 v[58:61], v[156:159], v[210:213], v[58:61]
	v_mfma_f32_16x16x32_bf16 v[54:57], v[148:151], v[218:221], v[54:57]
	v_mfma_f32_16x16x32_bf16 v[50:53], v[156:159], v[218:221], v[50:53]
	v_mfma_f32_16x16x32_bf16 v[38:41], v[148:151], v[226:229], v[38:41]
	v_mfma_f32_16x16x32_bf16 v[34:37], v[156:159], v[226:229], v[34:37]
	v_mfma_f32_16x16x32_bf16 v[22:25], v[148:151], v[234:237], v[22:25]
	v_mfma_f32_16x16x32_bf16 v[18:21], v[156:159], v[234:237], v[18:21]
	s_setprio 0
	s_setprio 1
	v_mfma_f32_16x16x32_bf16 v[46:49], v[160:163], v[206:209], v[46:49]
	v_mfma_f32_16x16x32_bf16 v[42:45], v[182:185], v[206:209], v[42:45]
	v_mfma_f32_16x16x32_bf16 v[30:33], v[160:163], v[214:217], v[30:33]
	v_mfma_f32_16x16x32_bf16 v[26:29], v[182:185], v[214:217], v[26:29]
	v_mfma_f32_16x16x32_bf16 v[14:17], v[160:163], v[222:225], v[14:17]
	v_mfma_f32_16x16x32_bf16 v[10:13], v[182:185], v[222:225], v[10:13]
	v_mfma_f32_16x16x32_bf16 v[6:9], v[160:163], v[230:233], v[6:9]
	v_mfma_f32_16x16x32_bf16 v[2:5], v[182:185], v[230:233], v[2:5]
	v_mfma_f32_16x16x32_bf16 v[46:49], v[178:181], v[210:213], v[46:49]
	v_mfma_f32_16x16x32_bf16 v[42:45], v[186:189], v[210:213], v[42:45]
	v_mfma_f32_16x16x32_bf16 v[30:33], v[178:181], v[218:221], v[30:33]
	v_mfma_f32_16x16x32_bf16 v[26:29], v[186:189], v[218:221], v[26:29]
	v_mfma_f32_16x16x32_bf16 v[14:17], v[178:181], v[226:229], v[14:17]
	v_mfma_f32_16x16x32_bf16 v[10:13], v[186:189], v[226:229], v[10:13]
	v_mfma_f32_16x16x32_bf16 v[6:9], v[178:181], v[234:237], v[6:9]
	v_mfma_f32_16x16x32_bf16 v[2:5], v[186:189], v[234:237], v[2:5]
	s_setprio 0
	s_add_i32 s84, s84, 2
	s_add_u32 s66, s66, 0x100
	s_addc_u32 s67, s67, 0
	s_add_u32 s82, s82, 0x100
	s_addc_u32 s83, s83, 0
	s_cmp_gt_u32 s84, 5
	s_barrier
	s_cbranch_scc0 .LBB0_426
	s_and_b64 vcc, exec, s[12:13]
	s_cbranch_vccz .LBB0_429
	s_barrier

.LBB0_442:
	s_add_u32 s62, s18, s72
	s_addc_u32 s63, s19, 0
	s_add_u32 s73, s62, 0x100
	s_addc_u32 s74, s63, 0
	s_and_b64 s[46:47], s[60:61], exec
	s_cselect_b32 s75, s23, s74
	s_cselect_b32 s74, s92, s73
	s_add_u32 s46, s16, s72
	s_addc_u32 s47, s17, 0
	s_add_u32 s72, s46, 0x100
	s_addc_u32 s73, s47, 0
	s_add_i32 s48, 0, 0x10000
	s_and_b64 s[46:47], s[60:61], exec
	s_cselect_b32 s77, s21, s73
	s_cselect_b32 s76, s93, s72
	s_add_i32 s46, 0, 0x14000
	s_add_u32 s80, s62, 0x10080
	s_addc_u32 s81, s63, 0
	s_add_i32 s63, s48, s84
	s_add_i32 m0, s13, 0xc000
	s_add_i32 s49, s13, 0xe000
	s_add_i32 vcc_lo, s63, 0x2000
	v_add_u32_e32 v139, s48, v136
	s_add_u32 s78, s76, 0x10000
	ds_read_b128 v[140:143], v139
	ds_read_b128 v[144:147], v139 offset:1024
	ds_read_b128 v[148:151], v139 offset:2048
	ds_read_b128 v[152:155], v139 offset:3072
	v_add_u32_e32 v139, s46, v136
	s_addc_u32 s79, s77, 0
	s_add_i32 vcc_hi, s46, s84
	ds_read_b128 v[156:159], v139
	ds_read_b128 v[160:163], v139 offset:1024
	ds_read_b128 v[178:181], v139 offset:2048
	ds_read_b128 v[182:185], v139 offset:3072
	s_add_i32 s62, vcc_hi, 0x2000
	s_add_i32 s97, 0, 0x18000
	s_add_i32 s96, 0, 0x1c000
	s_add_u32 s72, s74, 0x10000
	s_addc_u32 s73, s75, 0
	s_add_i32 s95, s97, s84
	s_add_i32 s94, s95, 0x2000
	s_add_u32 s60, s76, 0x10080
	s_addc_u32 s61, s77, 0
	s_add_i32 s47, s96, s84
	s_add_i32 s46, s47, 0x2000
	v_lshl_add_u64 v[164:165], s[80:81], 0, v[134:135]
	ds_read_b128 v[186:189], v138
	ds_read_b128 v[206:209], v138 offset:1024
	ds_read_b128 v[210:213], v138 offset:2048
	ds_read_b128 v[214:217], v138 offset:3072
	ds_read_b128 v[218:221], v138 offset:4096
	ds_read_b128 v[222:225], v138 offset:5120
	ds_read_b128 v[226:229], v138 offset:6144
	ds_read_b128 v[230:233], v138 offset:7168
	global_load_lds_dwordx4 v[164:165], off
	v_lshl_add_u64 v[164:165], s[80:81], 0, v[132:133]
	s_mov_b32 m0, s49
	s_nop 0
	global_load_lds_dwordx4 v[164:165], off
	s_waitcnt vmcnt(8)
	s_waitcnt lgkmcnt(0)
	s_setprio 1
	s_waitcnt lgkmcnt(0)
	v_mfma_f32_16x16x32_bf16 v[126:129], v[140:143], v[186:189], v[126:129]
	v_mfma_f32_16x16x32_bf16 v[122:125], v[148:151], v[186:189], v[122:125]
	v_mfma_f32_16x16x32_bf16 v[118:121], v[140:143], v[210:213], v[118:121]
	v_mfma_f32_16x16x32_bf16 v[114:117], v[148:151], v[210:213], v[114:117]
	s_barrier
	v_mfma_f32_16x16x32_bf16 v[102:105], v[140:143], v[218:221], v[102:105]
	v_mfma_f32_16x16x32_bf16 v[98:101], v[148:151], v[218:221], v[98:101]
	v_mfma_f32_16x16x32_bf16 v[86:89], v[140:143], v[226:229], v[86:89]
	v_mfma_f32_16x16x32_bf16 v[82:85], v[148:151], v[226:229], v[82:85]
	v_mfma_f32_16x16x32_bf16 v[126:129], v[144:147], v[206:209], v[126:129]
	v_mfma_f32_16x16x32_bf16 v[122:125], v[152:155], v[206:209], v[122:125]
	v_mfma_f32_16x16x32_bf16 v[118:121], v[144:147], v[214:217], v[118:121]
	v_mfma_f32_16x16x32_bf16 v[114:117], v[152:155], v[214:217], v[114:117]
	v_mfma_f32_16x16x32_bf16 v[102:105], v[144:147], v[222:225], v[102:105]
	v_mfma_f32_16x16x32_bf16 v[98:101], v[152:155], v[222:225], v[98:101]
	v_mfma_f32_16x16x32_bf16 v[86:89], v[144:147], v[230:233], v[86:89]
	v_mfma_f32_16x16x32_bf16 v[82:85], v[152:155], v[230:233], v[82:85]
	s_setprio 0
	s_setprio 1
	v_mfma_f32_16x16x32_bf16 v[110:113], v[156:159], v[186:189], v[110:113]
	v_mfma_f32_16x16x32_bf16 v[106:109], v[178:181], v[186:189], v[106:109]
	v_mfma_f32_16x16x32_bf16 v[94:97], v[156:159], v[210:213], v[94:97]
	v_mfma_f32_16x16x32_bf16 v[90:93], v[178:181], v[210:213], v[90:93]
	v_mfma_f32_16x16x32_bf16 v[78:81], v[156:159], v[218:221], v[78:81]
	v_mfma_f32_16x16x32_bf16 v[74:77], v[178:181], v[218:221], v[74:77]
	v_mfma_f32_16x16x32_bf16 v[70:73], v[156:159], v[226:229], v[70:73]
	v_mfma_f32_16x16x32_bf16 v[66:69], v[178:181], v[226:229], v[66:69]
	v_mfma_f32_16x16x32_bf16 v[110:113], v[160:163], v[206:209], v[110:113]
	v_mfma_f32_16x16x32_bf16 v[106:109], v[182:185], v[206:209], v[106:109]
	v_mfma_f32_16x16x32_bf16 v[94:97], v[160:163], v[214:217], v[94:97]
	v_mfma_f32_16x16x32_bf16 v[90:93], v[182:185], v[214:217], v[90:93]
	v_mfma_f32_16x16x32_bf16 v[78:81], v[160:163], v[222:225], v[78:81]
	v_mfma_f32_16x16x32_bf16 v[74:77], v[182:185], v[222:225], v[74:77]
	v_mfma_f32_16x16x32_bf16 v[70:73], v[160:163], v[230:233], v[70:73]
	v_mfma_f32_16x16x32_bf16 v[66:69], v[182:185], v[230:233], v[66:69]
	s_setprio 0
	s_mov_b32 m0, s63
	v_lshl_add_u64 v[164:165], s[76:77], 0, v[166:167]
	s_barrier
	ds_read_b128 v[186:189], v138 offset:16384
	ds_read_b128 v[206:209], v138 offset:17408
	ds_read_b128 v[210:213], v138 offset:18432
	ds_read_b128 v[214:217], v138 offset:19456
	ds_read_b128 v[218:221], v138 offset:20480
	ds_read_b128 v[222:225], v138 offset:21504
	ds_read_b128 v[226:229], v138 offset:22528
	ds_read_b128 v[230:233], v138 offset:23552
	global_load_lds_dwordx4 v[164:165], off
	v_lshl_add_u64 v[234:235], s[76:77], 0, v[130:131]
	s_mov_b32 m0, vcc_lo
	v_lshl_add_u64 v[236:237], s[78:79], 0, v[166:167]
	global_load_lds_dwordx4 v[234:235], off
	s_mov_b32 m0, vcc_hi
	v_lshl_add_u64 v[242:243], s[74:75], 0, v[132:133]
	global_load_lds_dwordx4 v[236:237], off
	v_lshl_add_u64 v[236:237], s[78:79], 0, v[130:131]
	s_mov_b32 m0, s62
	s_nop 0
	global_load_lds_dwordx4 v[236:237], off
	v_lshl_add_u64 v[236:237], s[74:75], 0, v[134:135]
	s_mov_b32 m0, s13
	s_nop 0
	global_load_lds_dwordx4 v[236:237], off
	s_mov_b32 m0, s86
	s_nop 0
	global_load_lds_dwordx4 v[242:243], off
	s_waitcnt vmcnt(8)
	s_waitcnt lgkmcnt(0)
	s_setprio 1
	s_waitcnt lgkmcnt(0)
	v_mfma_f32_16x16x32_bf16 v[62:65], v[140:143], v[186:189], v[62:65]
	v_mfma_f32_16x16x32_bf16 v[58:61], v[148:151], v[186:189], v[58:61]
	v_mfma_f32_16x16x32_bf16 v[54:57], v[140:143], v[210:213], v[54:57]
	v_mfma_f32_16x16x32_bf16 v[50:53], v[148:151], v[210:213], v[50:53]
	s_barrier
	v_mfma_f32_16x16x32_bf16 v[38:41], v[140:143], v[218:221], v[38:41]
	v_mfma_f32_16x16x32_bf16 v[34:37], v[148:151], v[218:221], v[34:37]
	v_mfma_f32_16x16x32_bf16 v[22:25], v[140:143], v[226:229], v[22:25]
	v_mfma_f32_16x16x32_bf16 v[18:21], v[148:151], v[226:229], v[18:21]
	v_mfma_f32_16x16x32_bf16 v[62:65], v[144:147], v[206:209], v[62:65]
	v_mfma_f32_16x16x32_bf16 v[58:61], v[152:155], v[206:209], v[58:61]
	v_mfma_f32_16x16x32_bf16 v[54:57], v[144:147], v[214:217], v[54:57]
	v_mfma_f32_16x16x32_bf16 v[50:53], v[152:155], v[214:217], v[50:53]
	v_mfma_f32_16x16x32_bf16 v[38:41], v[144:147], v[222:225], v[38:41]
	v_mfma_f32_16x16x32_bf16 v[34:37], v[152:155], v[222:225], v[34:37]
	v_mfma_f32_16x16x32_bf16 v[22:25], v[144:147], v[230:233], v[22:25]
	v_mfma_f32_16x16x32_bf16 v[18:21], v[152:155], v[230:233], v[18:21]
	s_setprio 0
	s_setprio 1
	v_mfma_f32_16x16x32_bf16 v[46:49], v[156:159], v[186:189], v[46:49]
	v_mfma_f32_16x16x32_bf16 v[42:45], v[178:181], v[186:189], v[42:45]
	v_mfma_f32_16x16x32_bf16 v[30:33], v[156:159], v[210:213], v[30:33]
	v_mfma_f32_16x16x32_bf16 v[26:29], v[178:181], v[210:213], v[26:29]
	v_mfma_f32_16x16x32_bf16 v[14:17], v[156:159], v[218:221], v[14:17]
	v_mfma_f32_16x16x32_bf16 v[10:13], v[178:181], v[218:221], v[10:13]
	v_mfma_f32_16x16x32_bf16 v[6:9], v[156:159], v[226:229], v[6:9]
	v_mfma_f32_16x16x32_bf16 v[2:5], v[178:181], v[226:229], v[2:5]
	v_mfma_f32_16x16x32_bf16 v[46:49], v[160:163], v[206:209], v[46:49]
	v_mfma_f32_16x16x32_bf16 v[42:45], v[182:185], v[206:209], v[42:45]
	v_mfma_f32_16x16x32_bf16 v[30:33], v[160:163], v[214:217], v[30:33]
	v_mfma_f32_16x16x32_bf16 v[26:29], v[182:185], v[214:217], v[26:29]
	v_mfma_f32_16x16x32_bf16 v[14:17], v[160:163], v[222:225], v[14:17]
	v_mfma_f32_16x16x32_bf16 v[10:13], v[182:185], v[222:225], v[10:13]
	v_mfma_f32_16x16x32_bf16 v[6:9], v[160:163], v[230:233], v[6:9]
	v_mfma_f32_16x16x32_bf16 v[2:5], v[182:185], v[230:233], v[2:5]
	s_setprio 0
	v_add_u32_e32 v139, s97, v136
	s_barrier
	ds_read_b128 v[140:143], v139
	ds_read_b128 v[144:147], v139 offset:1024
	ds_read_b128 v[148:151], v139 offset:2048
	ds_read_b128 v[152:155], v139 offset:3072
	v_add_u32_e32 v139, s96, v136
	ds_read_b128 v[156:159], v139
	ds_read_b128 v[160:163], v139 offset:1024
	ds_read_b128 v[178:181], v139 offset:2048
	ds_read_b128 v[182:185], v139 offset:3072
	s_mov_b32 m0, s87
	v_lshl_add_u64 v[244:245], s[72:73], 0, v[134:135]
	ds_read_b128 v[186:189], v138 offset:32768
	ds_read_b128 v[206:209], v138 offset:33792
	ds_read_b128 v[210:213], v138 offset:34816
	ds_read_b128 v[214:217], v138 offset:35840
	ds_read_b128 v[218:221], v138 offset:36864
	ds_read_b128 v[222:225], v138 offset:37888
	ds_read_b128 v[226:229], v138 offset:38912
	ds_read_b128 v[230:233], v138 offset:39936
	global_load_lds_dwordx4 v[244:245], off
	v_lshl_add_u64 v[244:245], s[72:73], 0, v[132:133]
	s_mov_b32 m0, s88
	s_nop 0
	global_load_lds_dwordx4 v[244:245], off
	s_waitcnt vmcnt(8)
	s_waitcnt lgkmcnt(0)
	s_setprio 1
	s_waitcnt lgkmcnt(0)
	v_mfma_f32_16x16x32_bf16 v[126:129], v[140:143], v[186:189], v[126:129]
	v_mfma_f32_16x16x32_bf16 v[122:125], v[148:151], v[186:189], v[122:125]
	v_mfma_f32_16x16x32_bf16 v[118:121], v[140:143], v[210:213], v[118:121]
	v_mfma_f32_16x16x32_bf16 v[114:117], v[148:151], v[210:213], v[114:117]
	s_barrier
	v_mfma_f32_16x16x32_bf16 v[102:105], v[140:143], v[218:221], v[102:105]
	v_mfma_f32_16x16x32_bf16 v[98:101], v[148:151], v[218:221], v[98:101]
	v_mfma_f32_16x16x32_bf16 v[86:89], v[140:143], v[226:229], v[86:89]
	v_mfma_f32_16x16x32_bf16 v[82:85], v[148:151], v[226:229], v[82:85]
	v_mfma_f32_16x16x32_bf16 v[126:129], v[144:147], v[206:209], v[126:129]
	v_mfma_f32_16x16x32_bf16 v[122:125], v[152:155], v[206:209], v[122:125]
	v_mfma_f32_16x16x32_bf16 v[118:121], v[144:147], v[214:217], v[118:121]
	v_mfma_f32_16x16x32_bf16 v[114:117], v[152:155], v[214:217], v[114:117]
	v_mfma_f32_16x16x32_bf16 v[102:105], v[144:147], v[222:225], v[102:105]
	v_mfma_f32_16x16x32_bf16 v[98:101], v[152:155], v[222:225], v[98:101]
	v_mfma_f32_16x16x32_bf16 v[86:89], v[144:147], v[230:233], v[86:89]
	v_mfma_f32_16x16x32_bf16 v[82:85], v[152:155], v[230:233], v[82:85]
	s_setprio 0
	s_setprio 1
	v_mfma_f32_16x16x32_bf16 v[110:113], v[156:159], v[186:189], v[110:113]
	v_mfma_f32_16x16x32_bf16 v[106:109], v[178:181], v[186:189], v[106:109]
	v_mfma_f32_16x16x32_bf16 v[94:97], v[156:159], v[210:213], v[94:97]
	v_mfma_f32_16x16x32_bf16 v[90:93], v[178:181], v[210:213], v[90:93]
	v_mfma_f32_16x16x32_bf16 v[78:81], v[156:159], v[218:221], v[78:81]
	v_mfma_f32_16x16x32_bf16 v[74:77], v[178:181], v[218:221], v[74:77]
	v_mfma_f32_16x16x32_bf16 v[70:73], v[156:159], v[226:229], v[70:73]
	v_mfma_f32_16x16x32_bf16 v[66:69], v[178:181], v[226:229], v[66:69]
	v_mfma_f32_16x16x32_bf16 v[110:113], v[160:163], v[206:209], v[110:113]
	v_mfma_f32_16x16x32_bf16 v[106:109], v[182:185], v[206:209], v[106:109]
	v_mfma_f32_16x16x32_bf16 v[94:97], v[160:163], v[214:217], v[94:97]
	v_mfma_f32_16x16x32_bf16 v[90:93], v[182:185], v[214:217], v[90:93]
	v_mfma_f32_16x16x32_bf16 v[78:81], v[160:163], v[222:225], v[78:81]
	v_mfma_f32_16x16x32_bf16 v[74:77], v[182:185], v[222:225], v[74:77]
	v_mfma_f32_16x16x32_bf16 v[70:73], v[160:163], v[230:233], v[70:73]
	v_mfma_f32_16x16x32_bf16 v[66:69], v[182:185], v[230:233], v[66:69]
	s_setprio 0
	s_mov_b32 m0, s95
	v_lshl_add_u64 v[164:165], v[164:165], 0, s[42:43]
	s_barrier
	ds_read_b128 v[186:189], v138 offset:49152
	ds_read_b128 v[206:209], v138 offset:50176
	ds_read_b128 v[210:213], v138 offset:51200
	ds_read_b128 v[214:217], v138 offset:52224
	ds_read_b128 v[218:221], v138 offset:53248
	ds_read_b128 v[222:225], v138 offset:54272
	ds_read_b128 v[226:229], v138 offset:55296
	ds_read_b128 v[230:233], v138 offset:56320
	global_load_lds_dwordx4 v[164:165], off
	v_lshl_add_u64 v[164:165], v[234:235], 0, s[42:43]
	s_mov_b32 m0, s94
	s_nop 0
	global_load_lds_dwordx4 v[164:165], off
	v_lshl_add_u64 v[164:165], s[60:61], 0, v[166:167]
	s_mov_b32 m0, s47
	s_nop 0
	global_load_lds_dwordx4 v[164:165], off
	v_lshl_add_u64 v[164:165], s[60:61], 0, v[130:131]
	s_mov_b32 m0, s46
	s_nop 0
	global_load_lds_dwordx4 v[164:165], off
	v_lshl_add_u64 v[164:165], v[236:237], 0, s[42:43]
	s_mov_b32 m0, s89
	s_nop 0
	global_load_lds_dwordx4 v[164:165], off
	v_lshl_add_u64 v[164:165], v[242:243], 0, s[42:43]
	s_mov_b32 m0, s90
	s_nop 0
	global_load_lds_dwordx4 v[164:165], off
	s_waitcnt vmcnt(8)
	s_waitcnt lgkmcnt(0)
	s_setprio 1
	s_waitcnt lgkmcnt(0)
	v_mfma_f32_16x16x32_bf16 v[62:65], v[140:143], v[186:189], v[62:65]
	v_mfma_f32_16x16x32_bf16 v[58:61], v[148:151], v[186:189], v[58:61]
	v_mfma_f32_16x16x32_bf16 v[54:57], v[140:143], v[210:213], v[54:57]
	v_mfma_f32_16x16x32_bf16 v[50:53], v[148:151], v[210:213], v[50:53]
	s_barrier
	v_mfma_f32_16x16x32_bf16 v[38:41], v[140:143], v[218:221], v[38:41]
	v_mfma_f32_16x16x32_bf16 v[34:37], v[148:151], v[218:221], v[34:37]
	v_mfma_f32_16x16x32_bf16 v[22:25], v[140:143], v[226:229], v[22:25]
	v_mfma_f32_16x16x32_bf16 v[18:21], v[148:151], v[226:229], v[18:21]
	v_mfma_f32_16x16x32_bf16 v[62:65], v[144:147], v[206:209], v[62:65]
	v_mfma_f32_16x16x32_bf16 v[58:61], v[152:155], v[206:209], v[58:61]
	v_mfma_f32_16x16x32_bf16 v[54:57], v[144:147], v[214:217], v[54:57]
	v_mfma_f32_16x16x32_bf16 v[50:53], v[152:155], v[214:217], v[50:53]
	v_mfma_f32_16x16x32_bf16 v[38:41], v[144:147], v[222:225], v[38:41]
	v_mfma_f32_16x16x32_bf16 v[34:37], v[152:155], v[222:225], v[34:37]
	v_mfma_f32_16x16x32_bf16 v[22:25], v[144:147], v[230:233], v[22:25]
	v_mfma_f32_16x16x32_bf16 v[18:21], v[152:155], v[230:233], v[18:21]
	s_setprio 0
	s_setprio 1
	v_mfma_f32_16x16x32_bf16 v[46:49], v[156:159], v[186:189], v[46:49]
	v_mfma_f32_16x16x32_bf16 v[42:45], v[178:181], v[186:189], v[42:45]
	v_mfma_f32_16x16x32_bf16 v[30:33], v[156:159], v[210:213], v[30:33]
	v_mfma_f32_16x16x32_bf16 v[26:29], v[178:181], v[210:213], v[26:29]
	v_mfma_f32_16x16x32_bf16 v[14:17], v[156:159], v[218:221], v[14:17]
	v_mfma_f32_16x16x32_bf16 v[10:13], v[178:181], v[218:221], v[10:13]
	v_mfma_f32_16x16x32_bf16 v[6:9], v[156:159], v[226:229], v[6:9]
	v_mfma_f32_16x16x32_bf16 v[2:5], v[178:181], v[226:229], v[2:5]
	v_mfma_f32_16x16x32_bf16 v[46:49], v[160:163], v[206:209], v[46:49]
	v_mfma_f32_16x16x32_bf16 v[42:45], v[182:185], v[206:209], v[42:45]
	v_mfma_f32_16x16x32_bf16 v[30:33], v[160:163], v[214:217], v[30:33]
	v_mfma_f32_16x16x32_bf16 v[26:29], v[182:185], v[214:217], v[26:29]
	v_mfma_f32_16x16x32_bf16 v[14:17], v[160:163], v[222:225], v[14:17]
	v_mfma_f32_16x16x32_bf16 v[10:13], v[182:185], v[222:225], v[10:13]
	v_mfma_f32_16x16x32_bf16 v[6:9], v[160:163], v[230:233], v[6:9]
	v_mfma_f32_16x16x32_bf16 v[2:5], v[182:185], v[230:233], v[2:5]
	s_setprio 0
	s_barrier
	s_movk_i32 s72, 0x100
	s_andn2_b64 vcc, exec, s[70:71]
	s_mov_b64 s[60:61], -1
	s_mov_b64 s[70:71], 0
	s_cbranch_vccz .LBB0_442
	s_and_b64 vcc, exec, s[10:11]
	s_cbranch_vccz .LBB0_445
	s_barrier

.LBB0_795:
	s_add_u32 s46, s68, 0xfff80080
	s_addc_u32 s47, s69, -1
	s_add_i32 s48, 0, 0x10000
	s_cmp_eq_u32 s87, 28
	s_cselect_b32 s71, s19, s47
	s_cselect_b32 s70, s83, s46
	s_cselect_b32 s61, s17, s86
	s_cselect_b32 s60, s84, s85
	s_add_i32 s49, 0, 0x14000
	v_add_u32_e32 v156, s48, v1
	v_add_u32_e32 v164, s49, v1
	ds_read_b128 v[130:133], v156
	ds_read_b128 v[134:137], v156 offset:1024
	ds_read_b128 v[150:153], v156 offset:2048
	ds_read_b128 v[156:159], v156 offset:3072
	ds_read_b128 v[160:163], v164
	ds_read_b128 v[178:181], v164 offset:1024
	ds_read_b128 v[182:185], v164 offset:2048
	ds_read_b128 v[186:189], v164 offset:3072
	v_lshl_add_u64 v[164:165], s[68:69], 0, v[146:147]
	s_add_i32 m0, s67, 0xc000
	ds_read_b128 v[206:209], v155
	ds_read_b128 v[210:213], v155 offset:1024
	ds_read_b128 v[214:217], v155 offset:2048
	ds_read_b128 v[218:221], v155 offset:3072
	ds_read_b128 v[222:225], v155 offset:4096
	ds_read_b128 v[226:229], v155 offset:5120
	ds_read_b128 v[230:233], v155 offset:6144
	ds_read_b128 v[234:237], v155 offset:7168
	global_load_lds_dwordx4 v[164:165], off
	v_lshl_add_u64 v[164:165], s[68:69], 0, v[148:149]
	s_add_i32 m0, s67, 0xe000
	s_nop 0
	global_load_lds_dwordx4 v[164:165], off
	s_waitcnt vmcnt(8)
	s_waitcnt lgkmcnt(0)
	s_setprio 1
	s_waitcnt lgkmcnt(0)
	v_mfma_f32_16x16x32_bf16 v[126:129], v[130:133], v[206:209], v[126:129]
	v_mfma_f32_16x16x32_bf16 v[122:125], v[150:153], v[206:209], v[122:125]
	v_mfma_f32_16x16x32_bf16 v[118:121], v[130:133], v[214:217], v[118:121]
	v_mfma_f32_16x16x32_bf16 v[114:117], v[150:153], v[214:217], v[114:117]
	s_barrier
	v_mfma_f32_16x16x32_bf16 v[110:113], v[130:133], v[222:225], v[110:113]
	v_mfma_f32_16x16x32_bf16 v[106:109], v[150:153], v[222:225], v[106:109]
	v_mfma_f32_16x16x32_bf16 v[102:105], v[130:133], v[230:233], v[102:105]
	v_mfma_f32_16x16x32_bf16 v[98:101], v[150:153], v[230:233], v[98:101]
	v_mfma_f32_16x16x32_bf16 v[126:129], v[134:137], v[210:213], v[126:129]
	v_mfma_f32_16x16x32_bf16 v[122:125], v[156:159], v[210:213], v[122:125]
	v_mfma_f32_16x16x32_bf16 v[118:121], v[134:137], v[218:221], v[118:121]
	v_mfma_f32_16x16x32_bf16 v[114:117], v[156:159], v[218:221], v[114:117]
	v_mfma_f32_16x16x32_bf16 v[110:113], v[134:137], v[226:229], v[110:113]
	v_mfma_f32_16x16x32_bf16 v[106:109], v[156:159], v[226:229], v[106:109]
	v_mfma_f32_16x16x32_bf16 v[102:105], v[134:137], v[234:237], v[102:105]
	v_mfma_f32_16x16x32_bf16 v[98:101], v[156:159], v[234:237], v[98:101]
	s_setprio 0
	s_setprio 1
	v_mfma_f32_16x16x32_bf16 v[66:69], v[160:163], v[206:209], v[66:69]
	v_mfma_f32_16x16x32_bf16 v[58:61], v[182:185], v[206:209], v[58:61]
	v_mfma_f32_16x16x32_bf16 v[54:57], v[160:163], v[214:217], v[54:57]
	v_mfma_f32_16x16x32_bf16 v[50:53], v[182:185], v[214:217], v[50:53]
	v_mfma_f32_16x16x32_bf16 v[46:49], v[160:163], v[222:225], v[46:49]
	v_mfma_f32_16x16x32_bf16 v[42:45], v[182:185], v[222:225], v[42:45]
	v_mfma_f32_16x16x32_bf16 v[38:41], v[160:163], v[230:233], v[38:41]
	v_mfma_f32_16x16x32_bf16 v[34:37], v[182:185], v[230:233], v[34:37]
	v_mfma_f32_16x16x32_bf16 v[66:69], v[178:181], v[210:213], v[66:69]
	v_mfma_f32_16x16x32_bf16 v[58:61], v[186:189], v[210:213], v[58:61]
	v_mfma_f32_16x16x32_bf16 v[54:57], v[178:181], v[218:221], v[54:57]
	v_mfma_f32_16x16x32_bf16 v[50:53], v[186:189], v[218:221], v[50:53]
	v_mfma_f32_16x16x32_bf16 v[46:49], v[178:181], v[226:229], v[46:49]
	v_mfma_f32_16x16x32_bf16 v[42:45], v[186:189], v[226:229], v[42:45]
	v_mfma_f32_16x16x32_bf16 v[38:41], v[178:181], v[234:237], v[38:41]
	v_mfma_f32_16x16x32_bf16 v[34:37], v[186:189], v[234:237], v[34:37]
	s_setprio 0
	s_add_i32 s46, s48, s77
	v_lshl_add_u64 v[164:165], s[60:61], 0, v[166:167]
	s_mov_b32 m0, s46
	s_barrier
	ds_read_b128 v[206:209], v155 offset:16384
	ds_read_b128 v[210:213], v155 offset:17408
	ds_read_b128 v[214:217], v155 offset:18432
	ds_read_b128 v[218:221], v155 offset:19456
	ds_read_b128 v[222:225], v155 offset:20480
	ds_read_b128 v[226:229], v155 offset:21504
	ds_read_b128 v[230:233], v155 offset:22528
	ds_read_b128 v[234:237], v155 offset:23552
	global_load_lds_dwordx4 v[164:165], off
	s_add_i32 m0, s46, 0x2000
	s_add_u32 s46, s60, 0x80000
	v_lshl_add_u64 v[242:243], s[60:61], 0, v[142:143]
	s_addc_u32 s47, s61, 0
	s_add_i32 s48, s49, s77
	global_load_lds_dwordx4 v[242:243], off
	v_lshl_add_u64 v[244:245], s[46:47], 0, v[166:167]
	s_mov_b32 m0, s48
	v_lshl_add_u64 v[246:247], s[70:71], 0, v[140:141]
	global_load_lds_dwordx4 v[244:245], off
	v_lshl_add_u64 v[244:245], s[46:47], 0, v[142:143]
	s_add_i32 m0, s48, 0x2000
	s_nop 0
	global_load_lds_dwordx4 v[244:245], off
	v_lshl_add_u64 v[244:245], s[70:71], 0, v[138:139]
	s_mov_b32 m0, s67
	s_nop 0
	global_load_lds_dwordx4 v[244:245], off
	s_mov_b32 m0, s78
	s_nop 0
	global_load_lds_dwordx4 v[246:247], off
	s_waitcnt vmcnt(8)
	s_waitcnt lgkmcnt(0)
	s_setprio 1
	s_waitcnt lgkmcnt(0)
	v_mfma_f32_16x16x32_bf16 v[94:97], v[130:133], v[206:209], v[94:97]
	v_mfma_f32_16x16x32_bf16 v[90:93], v[150:153], v[206:209], v[90:93]
	v_mfma_f32_16x16x32_bf16 v[86:89], v[130:133], v[214:217], v[86:89]
	v_mfma_f32_16x16x32_bf16 v[82:85], v[150:153], v[214:217], v[82:85]
	s_barrier
	v_mfma_f32_16x16x32_bf16 v[78:81], v[130:133], v[222:225], v[78:81]
	v_mfma_f32_16x16x32_bf16 v[74:77], v[150:153], v[222:225], v[74:77]
	v_mfma_f32_16x16x32_bf16 v[70:73], v[130:133], v[230:233], v[70:73]
	v_mfma_f32_16x16x32_bf16 v[62:65], v[150:153], v[230:233], v[62:65]
	v_mfma_f32_16x16x32_bf16 v[94:97], v[134:137], v[210:213], v[94:97]
	v_mfma_f32_16x16x32_bf16 v[90:93], v[156:159], v[210:213], v[90:93]
	v_mfma_f32_16x16x32_bf16 v[86:89], v[134:137], v[218:221], v[86:89]
	v_mfma_f32_16x16x32_bf16 v[82:85], v[156:159], v[218:221], v[82:85]
	v_mfma_f32_16x16x32_bf16 v[78:81], v[134:137], v[226:229], v[78:81]
	v_mfma_f32_16x16x32_bf16 v[74:77], v[156:159], v[226:229], v[74:77]
	v_mfma_f32_16x16x32_bf16 v[70:73], v[134:137], v[234:237], v[70:73]
	v_mfma_f32_16x16x32_bf16 v[62:65], v[156:159], v[234:237], v[62:65]
	s_setprio 0
	s_setprio 1
	v_mfma_f32_16x16x32_bf16 v[30:33], v[160:163], v[206:209], v[30:33]
	v_mfma_f32_16x16x32_bf16 v[26:29], v[182:185], v[206:209], v[26:29]
	v_mfma_f32_16x16x32_bf16 v[22:25], v[160:163], v[214:217], v[22:25]
	v_mfma_f32_16x16x32_bf16 v[18:21], v[182:185], v[214:217], v[18:21]
	v_mfma_f32_16x16x32_bf16 v[14:17], v[160:163], v[222:225], v[14:17]
	v_mfma_f32_16x16x32_bf16 v[10:13], v[182:185], v[222:225], v[10:13]
	v_mfma_f32_16x16x32_bf16 v[6:9], v[160:163], v[230:233], v[6:9]
	v_mfma_f32_16x16x32_bf16 v[2:5], v[182:185], v[230:233], v[2:5]
	v_mfma_f32_16x16x32_bf16 v[30:33], v[178:181], v[210:213], v[30:33]
	v_mfma_f32_16x16x32_bf16 v[26:29], v[186:189], v[210:213], v[26:29]
	v_mfma_f32_16x16x32_bf16 v[22:25], v[178:181], v[218:221], v[22:25]
	v_mfma_f32_16x16x32_bf16 v[18:21], v[186:189], v[218:221], v[18:21]
	v_mfma_f32_16x16x32_bf16 v[14:17], v[178:181], v[226:229], v[14:17]
	v_mfma_f32_16x16x32_bf16 v[10:13], v[186:189], v[226:229], v[10:13]
	v_mfma_f32_16x16x32_bf16 v[6:9], v[178:181], v[234:237], v[6:9]
	v_mfma_f32_16x16x32_bf16 v[2:5], v[186:189], v[234:237], v[2:5]
	s_setprio 0
	s_add_i32 s48, 0, 0x18000
	s_add_i32 s49, 0, 0x1c000
	v_add_u32_e32 v156, s48, v1
	v_add_u32_e32 v186, s49, v1
	s_barrier
	ds_read_b128 v[130:133], v156
	ds_read_b128 v[134:137], v156 offset:1024
	ds_read_b128 v[150:153], v156 offset:2048
	ds_read_b128 v[156:159], v156 offset:3072
	ds_read_b128 v[160:163], v186
	ds_read_b128 v[178:181], v186 offset:1024
	ds_read_b128 v[182:185], v186 offset:2048
	ds_read_b128 v[186:189], v186 offset:3072
	s_add_u32 s46, s70, 0x80000
	s_addc_u32 s47, s71, 0
	s_mov_b32 m0, s79
	v_lshl_add_u64 v[248:249], s[46:47], 0, v[138:139]
	ds_read_b128 v[206:209], v155 offset:32768
	ds_read_b128 v[210:213], v155 offset:33792
	ds_read_b128 v[214:217], v155 offset:34816
	ds_read_b128 v[218:221], v155 offset:35840
	ds_read_b128 v[222:225], v155 offset:36864
	ds_read_b128 v[226:229], v155 offset:37888
	ds_read_b128 v[230:233], v155 offset:38912
	ds_read_b128 v[234:237], v155 offset:39936
	global_load_lds_dwordx4 v[248:249], off
	v_lshl_add_u64 v[248:249], s[46:47], 0, v[140:141]
	s_mov_b32 m0, s80
	s_nop 0
	global_load_lds_dwordx4 v[248:249], off
	s_waitcnt vmcnt(8)
	s_waitcnt lgkmcnt(0)
	s_setprio 1
	s_waitcnt lgkmcnt(0)
	v_mfma_f32_16x16x32_bf16 v[126:129], v[130:133], v[206:209], v[126:129]
	v_mfma_f32_16x16x32_bf16 v[122:125], v[150:153], v[206:209], v[122:125]
	v_mfma_f32_16x16x32_bf16 v[118:121], v[130:133], v[214:217], v[118:121]
	v_mfma_f32_16x16x32_bf16 v[114:117], v[150:153], v[214:217], v[114:117]
	s_barrier
	v_mfma_f32_16x16x32_bf16 v[110:113], v[130:133], v[222:225], v[110:113]
	v_mfma_f32_16x16x32_bf16 v[106:109], v[150:153], v[222:225], v[106:109]
	v_mfma_f32_16x16x32_bf16 v[102:105], v[130:133], v[230:233], v[102:105]
	v_mfma_f32_16x16x32_bf16 v[98:101], v[150:153], v[230:233], v[98:101]
	v_mfma_f32_16x16x32_bf16 v[126:129], v[134:137], v[210:213], v[126:129]
	v_mfma_f32_16x16x32_bf16 v[122:125], v[156:159], v[210:213], v[122:125]
	v_mfma_f32_16x16x32_bf16 v[118:121], v[134:137], v[218:221], v[118:121]
	v_mfma_f32_16x16x32_bf16 v[114:117], v[156:159], v[218:221], v[114:117]
	v_mfma_f32_16x16x32_bf16 v[110:113], v[134:137], v[226:229], v[110:113]
	v_mfma_f32_16x16x32_bf16 v[106:109], v[156:159], v[226:229], v[106:109]
	v_mfma_f32_16x16x32_bf16 v[102:105], v[134:137], v[234:237], v[102:105]
	v_mfma_f32_16x16x32_bf16 v[98:101], v[156:159], v[234:237], v[98:101]
	s_setprio 0
	s_setprio 1
	v_mfma_f32_16x16x32_bf16 v[66:69], v[160:163], v[206:209], v[66:69]
	v_mfma_f32_16x16x32_bf16 v[58:61], v[182:185], v[206:209], v[58:61]
	v_mfma_f32_16x16x32_bf16 v[54:57], v[160:163], v[214:217], v[54:57]
	v_mfma_f32_16x16x32_bf16 v[50:53], v[182:185], v[214:217], v[50:53]
	v_mfma_f32_16x16x32_bf16 v[46:49], v[160:163], v[222:225], v[46:49]
	v_mfma_f32_16x16x32_bf16 v[42:45], v[182:185], v[222:225], v[42:45]
	v_mfma_f32_16x16x32_bf16 v[38:41], v[160:163], v[230:233], v[38:41]
	v_mfma_f32_16x16x32_bf16 v[34:37], v[182:185], v[230:233], v[34:37]
	v_mfma_f32_16x16x32_bf16 v[66:69], v[178:181], v[210:213], v[66:69]
	v_mfma_f32_16x16x32_bf16 v[58:61], v[186:189], v[210:213], v[58:61]
	v_mfma_f32_16x16x32_bf16 v[54:57], v[178:181], v[218:221], v[54:57]
	v_mfma_f32_16x16x32_bf16 v[50:53], v[186:189], v[218:221], v[50:53]
	v_mfma_f32_16x16x32_bf16 v[46:49], v[178:181], v[226:229], v[46:49]
	v_mfma_f32_16x16x32_bf16 v[42:45], v[186:189], v[226:229], v[42:45]
	v_mfma_f32_16x16x32_bf16 v[38:41], v[178:181], v[234:237], v[38:41]
	v_mfma_f32_16x16x32_bf16 v[34:37], v[186:189], v[234:237], v[34:37]
	s_setprio 0
	s_add_i32 s46, s48, s77
	v_lshl_add_u64 v[164:165], v[164:165], 0, s[42:43]
	s_mov_b32 m0, s46
	s_barrier
	ds_read_b128 v[206:209], v155 offset:49152
	ds_read_b128 v[210:213], v155 offset:50176
	ds_read_b128 v[214:217], v155 offset:51200
	ds_read_b128 v[218:221], v155 offset:52224
	ds_read_b128 v[222:225], v155 offset:53248
	ds_read_b128 v[226:229], v155 offset:54272
	ds_read_b128 v[230:233], v155 offset:55296
	ds_read_b128 v[234:237], v155 offset:56320
	global_load_lds_dwordx4 v[164:165], off
	s_add_i32 m0, s46, 0x2000
	s_add_u32 s46, s60, 0x80080
	v_lshl_add_u64 v[164:165], v[242:243], 0, s[42:43]
	s_addc_u32 s47, s61, 0
	s_add_i32 s48, s49, s77
	global_load_lds_dwordx4 v[164:165], off
	v_lshl_add_u64 v[164:165], s[46:47], 0, v[166:167]
	s_mov_b32 m0, s48
	s_nop 0
	global_load_lds_dwordx4 v[164:165], off
	v_lshl_add_u64 v[164:165], s[46:47], 0, v[142:143]
	s_add_i32 m0, s48, 0x2000
	s_nop 0
	global_load_lds_dwordx4 v[164:165], off
	v_lshl_add_u64 v[164:165], v[244:245], 0, s[42:43]
	s_mov_b32 m0, s26
	s_nop 0
	global_load_lds_dwordx4 v[164:165], off
	v_lshl_add_u64 v[164:165], v[246:247], 0, s[42:43]
	s_mov_b32 m0, s81
	s_nop 0
	global_load_lds_dwordx4 v[164:165], off
	s_waitcnt vmcnt(8)
	s_waitcnt lgkmcnt(0)
	s_setprio 1
	s_waitcnt lgkmcnt(0)
	v_mfma_f32_16x16x32_bf16 v[94:97], v[130:133], v[206:209], v[94:97]
	v_mfma_f32_16x16x32_bf16 v[90:93], v[150:153], v[206:209], v[90:93]
	v_mfma_f32_16x16x32_bf16 v[86:89], v[130:133], v[214:217], v[86:89]
	v_mfma_f32_16x16x32_bf16 v[82:85], v[150:153], v[214:217], v[82:85]
	s_barrier
	v_mfma_f32_16x16x32_bf16 v[78:81], v[130:133], v[222:225], v[78:81]
	v_mfma_f32_16x16x32_bf16 v[74:77], v[150:153], v[222:225], v[74:77]
	v_mfma_f32_16x16x32_bf16 v[70:73], v[130:133], v[230:233], v[70:73]
	v_mfma_f32_16x16x32_bf16 v[62:65], v[150:153], v[230:233], v[62:65]
	v_mfma_f32_16x16x32_bf16 v[94:97], v[134:137], v[210:213], v[94:97]
	v_mfma_f32_16x16x32_bf16 v[90:93], v[156:159], v[210:213], v[90:93]
	v_mfma_f32_16x16x32_bf16 v[86:89], v[134:137], v[218:221], v[86:89]
	v_mfma_f32_16x16x32_bf16 v[82:85], v[156:159], v[218:221], v[82:85]
	v_mfma_f32_16x16x32_bf16 v[78:81], v[134:137], v[226:229], v[78:81]
	v_mfma_f32_16x16x32_bf16 v[74:77], v[156:159], v[226:229], v[74:77]
	v_mfma_f32_16x16x32_bf16 v[70:73], v[134:137], v[234:237], v[70:73]
	v_mfma_f32_16x16x32_bf16 v[62:65], v[156:159], v[234:237], v[62:65]
	s_setprio 0
	s_setprio 1
	v_mfma_f32_16x16x32_bf16 v[30:33], v[160:163], v[206:209], v[30:33]
	v_mfma_f32_16x16x32_bf16 v[26:29], v[182:185], v[206:209], v[26:29]
	v_mfma_f32_16x16x32_bf16 v[22:25], v[160:163], v[214:217], v[22:25]
	v_mfma_f32_16x16x32_bf16 v[18:21], v[182:185], v[214:217], v[18:21]
	v_mfma_f32_16x16x32_bf16 v[14:17], v[160:163], v[222:225], v[14:17]
	v_mfma_f32_16x16x32_bf16 v[10:13], v[182:185], v[222:225], v[10:13]
	v_mfma_f32_16x16x32_bf16 v[6:9], v[160:163], v[230:233], v[6:9]
	v_mfma_f32_16x16x32_bf16 v[2:5], v[182:185], v[230:233], v[2:5]
	v_mfma_f32_16x16x32_bf16 v[30:33], v[178:181], v[210:213], v[30:33]
	v_mfma_f32_16x16x32_bf16 v[26:29], v[186:189], v[210:213], v[26:29]
	v_mfma_f32_16x16x32_bf16 v[22:25], v[178:181], v[218:221], v[22:25]
	v_mfma_f32_16x16x32_bf16 v[18:21], v[186:189], v[218:221], v[18:21]
	v_mfma_f32_16x16x32_bf16 v[14:17], v[178:181], v[226:229], v[14:17]
	v_mfma_f32_16x16x32_bf16 v[10:13], v[186:189], v[226:229], v[10:13]
	v_mfma_f32_16x16x32_bf16 v[6:9], v[178:181], v[234:237], v[6:9]
	v_mfma_f32_16x16x32_bf16 v[2:5], v[186:189], v[234:237], v[2:5]
	s_setprio 0
	s_add_i32 s87, s87, 2
	s_add_u32 s68, s68, 0x100
	s_addc_u32 s69, s69, 0
	s_add_u32 s85, s85, 0x100
	s_addc_u32 s86, s86, 0
	s_cmp_gt_u32 s87, 29
	s_barrier
	s_cbranch_scc0 .LBB0_795
	s_and_b64 vcc, exec, s[12:13]
	s_cbranch_vccz .LBB0_798
	s_barrier

.LBB0_819:
	s_add_i32 s93, s60, 2
	s_add_u32 s46, s72, 0x80
	s_addc_u32 s47, s73, 0
	s_add_i32 s48, 0, 0x10000
	s_cmp_eq_u32 s87, s60
	s_cselect_b32 s61, s23, s47
	s_cselect_b32 s60, s64, s46
	s_cselect_b32 s47, s21, s92
	s_cselect_b32 s46, s90, s91
	s_add_i32 s49, 0, 0x14000
	v_add_u32_e32 v142, s48, v205
	v_add_u32_e32 v182, s49, v205
	ds_read_b128 v[130:133], v142
	ds_read_b128 v[134:137], v142 offset:1024
	ds_read_b128 v[138:141], v142 offset:2048
	ds_read_b128 v[142:145], v142 offset:3072
	ds_read_b128 v[146:149], v182
	ds_read_b128 v[150:153], v182 offset:1024
	ds_read_b128 v[178:181], v182 offset:2048
	ds_read_b128 v[182:185], v182 offset:3072
	v_lshl_add_u64 v[236:237], s[72:73], 0, v[162:163]
	s_add_i32 m0, s71, 0xc000
	ds_read_b128 v[186:189], v207
	ds_read_b128 v[208:211], v207 offset:1024
	ds_read_b128 v[212:215], v207 offset:2048
	ds_read_b128 v[216:219], v207 offset:3072
	ds_read_b128 v[220:223], v207 offset:4096
	ds_read_b128 v[224:227], v207 offset:5120
	ds_read_b128 v[228:231], v207 offset:6144
	ds_read_b128 v[232:235], v207 offset:7168
	global_load_lds_dwordx4 v[236:237], off
	v_lshl_add_u64 v[236:237], s[72:73], 0, v[164:165]
	s_add_i32 m0, s71, 0xe000
	s_nop 0
	global_load_lds_dwordx4 v[236:237], off
	s_waitcnt vmcnt(8)
	s_waitcnt lgkmcnt(0)
	s_setprio 1
	s_waitcnt lgkmcnt(0)
	v_mfma_f32_16x16x32_bf16 v[126:129], v[130:133], v[186:189], v[126:129]
	v_mfma_f32_16x16x32_bf16 v[122:125], v[138:141], v[186:189], v[122:125]
	v_mfma_f32_16x16x32_bf16 v[118:121], v[130:133], v[212:215], v[118:121]
	v_mfma_f32_16x16x32_bf16 v[114:117], v[138:141], v[212:215], v[114:117]
	s_barrier
	v_mfma_f32_16x16x32_bf16 v[110:113], v[130:133], v[220:223], v[110:113]
	v_mfma_f32_16x16x32_bf16 v[106:109], v[138:141], v[220:223], v[106:109]
	v_mfma_f32_16x16x32_bf16 v[102:105], v[130:133], v[228:231], v[102:105]
	v_mfma_f32_16x16x32_bf16 v[98:101], v[138:141], v[228:231], v[98:101]
	v_mfma_f32_16x16x32_bf16 v[126:129], v[134:137], v[208:211], v[126:129]
	v_mfma_f32_16x16x32_bf16 v[122:125], v[142:145], v[208:211], v[122:125]
	v_mfma_f32_16x16x32_bf16 v[118:121], v[134:137], v[216:219], v[118:121]
	v_mfma_f32_16x16x32_bf16 v[114:117], v[142:145], v[216:219], v[114:117]
	v_mfma_f32_16x16x32_bf16 v[110:113], v[134:137], v[224:227], v[110:113]
	v_mfma_f32_16x16x32_bf16 v[106:109], v[142:145], v[224:227], v[106:109]
	v_mfma_f32_16x16x32_bf16 v[102:105], v[134:137], v[232:235], v[102:105]
	v_mfma_f32_16x16x32_bf16 v[98:101], v[142:145], v[232:235], v[98:101]
	s_setprio 0
	s_setprio 1
	v_mfma_f32_16x16x32_bf16 v[94:97], v[146:149], v[186:189], v[94:97]
	v_mfma_f32_16x16x32_bf16 v[90:93], v[178:181], v[186:189], v[90:93]
	v_mfma_f32_16x16x32_bf16 v[86:89], v[146:149], v[212:215], v[86:89]
	v_mfma_f32_16x16x32_bf16 v[82:85], v[178:181], v[212:215], v[82:85]
	v_mfma_f32_16x16x32_bf16 v[78:81], v[146:149], v[220:223], v[78:81]
	v_mfma_f32_16x16x32_bf16 v[74:77], v[178:181], v[220:223], v[74:77]
	v_mfma_f32_16x16x32_bf16 v[70:73], v[146:149], v[228:231], v[70:73]
	v_mfma_f32_16x16x32_bf16 v[66:69], v[178:181], v[228:231], v[66:69]
	v_mfma_f32_16x16x32_bf16 v[94:97], v[150:153], v[208:211], v[94:97]
	v_mfma_f32_16x16x32_bf16 v[90:93], v[182:185], v[208:211], v[90:93]
	v_mfma_f32_16x16x32_bf16 v[86:89], v[150:153], v[216:219], v[86:89]
	v_mfma_f32_16x16x32_bf16 v[82:85], v[182:185], v[216:219], v[82:85]
	v_mfma_f32_16x16x32_bf16 v[78:81], v[150:153], v[224:227], v[78:81]
	v_mfma_f32_16x16x32_bf16 v[74:77], v[182:185], v[224:227], v[74:77]
	v_mfma_f32_16x16x32_bf16 v[70:73], v[150:153], v[232:235], v[70:73]
	v_mfma_f32_16x16x32_bf16 v[66:69], v[182:185], v[232:235], v[66:69]
	s_setprio 0
	s_add_i32 s48, s48, s80
	v_lshl_add_u64 v[236:237], s[46:47], 0, v[166:167]
	s_mov_b32 m0, s48
	s_barrier
	ds_read_b128 v[186:189], v207 offset:16384
	ds_read_b128 v[208:211], v207 offset:17408
	ds_read_b128 v[212:215], v207 offset:18432
	ds_read_b128 v[216:219], v207 offset:19456
	ds_read_b128 v[220:223], v207 offset:20480
	ds_read_b128 v[224:227], v207 offset:21504
	ds_read_b128 v[228:231], v207 offset:22528
	ds_read_b128 v[232:235], v207 offset:23552
	global_load_lds_dwordx4 v[236:237], off
	s_add_i32 m0, s48, 0x2000
	v_lshl_add_u64 v[242:243], s[46:47], 0, v[158:159]
	s_add_u32 s46, s46, s26
	s_addc_u32 s47, s47, 0
	s_add_i32 s48, s49, s80
	global_load_lds_dwordx4 v[242:243], off
	v_lshl_add_u64 v[244:245], s[46:47], 0, v[166:167]
	s_mov_b32 m0, s48
	v_lshl_add_u64 v[246:247], s[46:47], 0, v[158:159]
	global_load_lds_dwordx4 v[244:245], off
	s_add_i32 m0, s48, 0x2000
	v_lshl_add_u64 v[248:249], s[60:61], 0, v[154:155]
	global_load_lds_dwordx4 v[246:247], off
	s_mov_b32 m0, s71
	v_lshl_add_u64 v[250:251], s[60:61], 0, v[156:157]
	global_load_lds_dwordx4 v[248:249], off
	s_mov_b32 m0, s81
	s_nop 0
	global_load_lds_dwordx4 v[250:251], off
	s_waitcnt vmcnt(8)
	s_waitcnt lgkmcnt(0)
	s_setprio 1
	s_waitcnt lgkmcnt(0)
	v_mfma_f32_16x16x32_bf16 v[62:65], v[130:133], v[186:189], v[62:65]
	v_mfma_f32_16x16x32_bf16 v[58:61], v[138:141], v[186:189], v[58:61]
	v_mfma_f32_16x16x32_bf16 v[54:57], v[130:133], v[212:215], v[54:57]
	v_mfma_f32_16x16x32_bf16 v[50:53], v[138:141], v[212:215], v[50:53]
	s_barrier
	v_mfma_f32_16x16x32_bf16 v[46:49], v[130:133], v[220:223], v[46:49]
	v_mfma_f32_16x16x32_bf16 v[42:45], v[138:141], v[220:223], v[42:45]
	v_mfma_f32_16x16x32_bf16 v[38:41], v[130:133], v[228:231], v[38:41]
	v_mfma_f32_16x16x32_bf16 v[34:37], v[138:141], v[228:231], v[34:37]
	v_mfma_f32_16x16x32_bf16 v[62:65], v[134:137], v[208:211], v[62:65]
	v_mfma_f32_16x16x32_bf16 v[58:61], v[142:145], v[208:211], v[58:61]
	v_mfma_f32_16x16x32_bf16 v[54:57], v[134:137], v[216:219], v[54:57]
	v_mfma_f32_16x16x32_bf16 v[50:53], v[142:145], v[216:219], v[50:53]
	v_mfma_f32_16x16x32_bf16 v[46:49], v[134:137], v[224:227], v[46:49]
	v_mfma_f32_16x16x32_bf16 v[42:45], v[142:145], v[224:227], v[42:45]
	v_mfma_f32_16x16x32_bf16 v[38:41], v[134:137], v[232:235], v[38:41]
	v_mfma_f32_16x16x32_bf16 v[34:37], v[142:145], v[232:235], v[34:37]
	s_setprio 0
	s_setprio 1
	v_mfma_f32_16x16x32_bf16 v[30:33], v[146:149], v[186:189], v[30:33]
	v_mfma_f32_16x16x32_bf16 v[26:29], v[178:181], v[186:189], v[26:29]
	v_mfma_f32_16x16x32_bf16 v[22:25], v[146:149], v[212:215], v[22:25]
	v_mfma_f32_16x16x32_bf16 v[18:21], v[178:181], v[212:215], v[18:21]
	v_mfma_f32_16x16x32_bf16 v[14:17], v[146:149], v[220:223], v[14:17]
	v_mfma_f32_16x16x32_bf16 v[10:13], v[178:181], v[220:223], v[10:13]
	v_mfma_f32_16x16x32_bf16 v[6:9], v[146:149], v[228:231], v[6:9]
	v_mfma_f32_16x16x32_bf16 v[2:5], v[178:181], v[228:231], v[2:5]
	v_mfma_f32_16x16x32_bf16 v[30:33], v[150:153], v[208:211], v[30:33]
	v_mfma_f32_16x16x32_bf16 v[26:29], v[182:185], v[208:211], v[26:29]
	v_mfma_f32_16x16x32_bf16 v[22:25], v[150:153], v[216:219], v[22:25]
	v_mfma_f32_16x16x32_bf16 v[18:21], v[182:185], v[216:219], v[18:21]
	v_mfma_f32_16x16x32_bf16 v[14:17], v[150:153], v[224:227], v[14:17]
	v_mfma_f32_16x16x32_bf16 v[10:13], v[182:185], v[224:227], v[10:13]
	v_mfma_f32_16x16x32_bf16 v[6:9], v[150:153], v[232:235], v[6:9]
	v_mfma_f32_16x16x32_bf16 v[2:5], v[182:185], v[232:235], v[2:5]
	s_setprio 0
	s_add_i32 s48, 0, 0x18000
	s_add_i32 s49, 0, 0x1c000
	v_add_u32_e32 v142, s48, v205
	v_add_u32_e32 v182, s49, v205
	s_barrier
	ds_read_b128 v[130:133], v142
	ds_read_b128 v[134:137], v142 offset:1024
	ds_read_b128 v[138:141], v142 offset:2048
	ds_read_b128 v[142:145], v142 offset:3072
	ds_read_b128 v[146:149], v182
	ds_read_b128 v[150:153], v182 offset:1024
	ds_read_b128 v[178:181], v182 offset:2048
	ds_read_b128 v[182:185], v182 offset:3072
	s_add_u32 s46, s60, s26
	s_addc_u32 s47, s61, 0
	s_mov_b32 m0, s82
	v_lshl_add_u64 v[252:253], s[46:47], 0, v[154:155]
	ds_read_b128 v[186:189], v207 offset:32768
	ds_read_b128 v[208:211], v207 offset:33792
	ds_read_b128 v[212:215], v207 offset:34816
	ds_read_b128 v[216:219], v207 offset:35840
	ds_read_b128 v[220:223], v207 offset:36864
	ds_read_b128 v[224:227], v207 offset:37888
	ds_read_b128 v[228:231], v207 offset:38912
	ds_read_b128 v[232:235], v207 offset:39936
	global_load_lds_dwordx4 v[252:253], off
	v_lshl_add_u64 v[252:253], s[46:47], 0, v[156:157]
	s_mov_b32 m0, s83
	s_nop 0
	global_load_lds_dwordx4 v[252:253], off
	s_waitcnt vmcnt(8)
	s_waitcnt lgkmcnt(0)
	s_setprio 1
	s_waitcnt lgkmcnt(0)
	v_mfma_f32_16x16x32_bf16 v[126:129], v[130:133], v[186:189], v[126:129]
	v_mfma_f32_16x16x32_bf16 v[122:125], v[138:141], v[186:189], v[122:125]
	v_mfma_f32_16x16x32_bf16 v[118:121], v[130:133], v[212:215], v[118:121]
	v_mfma_f32_16x16x32_bf16 v[114:117], v[138:141], v[212:215], v[114:117]
	s_barrier
	v_mfma_f32_16x16x32_bf16 v[110:113], v[130:133], v[220:223], v[110:113]
	v_mfma_f32_16x16x32_bf16 v[106:109], v[138:141], v[220:223], v[106:109]
	v_mfma_f32_16x16x32_bf16 v[102:105], v[130:133], v[228:231], v[102:105]
	v_mfma_f32_16x16x32_bf16 v[98:101], v[138:141], v[228:231], v[98:101]
	v_mfma_f32_16x16x32_bf16 v[126:129], v[134:137], v[208:211], v[126:129]
	v_mfma_f32_16x16x32_bf16 v[122:125], v[142:145], v[208:211], v[122:125]
	v_mfma_f32_16x16x32_bf16 v[118:121], v[134:137], v[216:219], v[118:121]
	v_mfma_f32_16x16x32_bf16 v[114:117], v[142:145], v[216:219], v[114:117]
	v_mfma_f32_16x16x32_bf16 v[110:113], v[134:137], v[224:227], v[110:113]
	v_mfma_f32_16x16x32_bf16 v[106:109], v[142:145], v[224:227], v[106:109]
	v_mfma_f32_16x16x32_bf16 v[102:105], v[134:137], v[232:235], v[102:105]
	v_mfma_f32_16x16x32_bf16 v[98:101], v[142:145], v[232:235], v[98:101]
	s_setprio 0
	s_setprio 1
	v_mfma_f32_16x16x32_bf16 v[94:97], v[146:149], v[186:189], v[94:97]
	v_mfma_f32_16x16x32_bf16 v[90:93], v[178:181], v[186:189], v[90:93]
	v_mfma_f32_16x16x32_bf16 v[86:89], v[146:149], v[212:215], v[86:89]
	v_mfma_f32_16x16x32_bf16 v[82:85], v[178:181], v[212:215], v[82:85]
	v_mfma_f32_16x16x32_bf16 v[78:81], v[146:149], v[220:223], v[78:81]
	v_mfma_f32_16x16x32_bf16 v[74:77], v[178:181], v[220:223], v[74:77]
	v_mfma_f32_16x16x32_bf16 v[70:73], v[146:149], v[228:231], v[70:73]
	v_mfma_f32_16x16x32_bf16 v[66:69], v[178:181], v[228:231], v[66:69]
	v_mfma_f32_16x16x32_bf16 v[94:97], v[150:153], v[208:211], v[94:97]
	v_mfma_f32_16x16x32_bf16 v[90:93], v[182:185], v[208:211], v[90:93]
	v_mfma_f32_16x16x32_bf16 v[86:89], v[150:153], v[216:219], v[86:89]
	v_mfma_f32_16x16x32_bf16 v[82:85], v[182:185], v[216:219], v[82:85]
	v_mfma_f32_16x16x32_bf16 v[78:81], v[150:153], v[224:227], v[78:81]
	v_mfma_f32_16x16x32_bf16 v[74:77], v[182:185], v[224:227], v[74:77]
	v_mfma_f32_16x16x32_bf16 v[70:73], v[150:153], v[232:235], v[70:73]
	v_mfma_f32_16x16x32_bf16 v[66:69], v[182:185], v[232:235], v[66:69]
	s_setprio 0
	s_add_i32 s46, s48, s80
	v_lshl_add_u64 v[236:237], v[236:237], 0, s[42:43]
	s_mov_b32 m0, s46
	s_barrier
	ds_read_b128 v[186:189], v207 offset:49152
	ds_read_b128 v[208:211], v207 offset:50176
	ds_read_b128 v[212:215], v207 offset:51200
	ds_read_b128 v[216:219], v207 offset:52224
	ds_read_b128 v[220:223], v207 offset:53248
	ds_read_b128 v[224:227], v207 offset:54272
	ds_read_b128 v[228:231], v207 offset:55296
	ds_read_b128 v[232:235], v207 offset:56320
	global_load_lds_dwordx4 v[236:237], off
	v_lshl_add_u64 v[236:237], v[242:243], 0, s[42:43]
	s_add_i32 m0, s46, 0x2000
	s_add_i32 s46, s49, s80
	global_load_lds_dwordx4 v[236:237], off
	v_lshl_add_u64 v[236:237], v[244:245], 0, s[42:43]
	s_mov_b32 m0, s46
	s_nop 0
	global_load_lds_dwordx4 v[236:237], off
	v_lshl_add_u64 v[236:237], v[246:247], 0, s[42:43]
	s_add_i32 m0, s46, 0x2000
	s_nop 0
	global_load_lds_dwordx4 v[236:237], off
	v_lshl_add_u64 v[236:237], v[248:249], 0, s[42:43]
	s_mov_b32 m0, s85
	s_nop 0
	global_load_lds_dwordx4 v[236:237], off
	v_lshl_add_u64 v[236:237], v[250:251], 0, s[42:43]
	s_mov_b32 m0, s86
	s_nop 0
	global_load_lds_dwordx4 v[236:237], off
	s_waitcnt vmcnt(8)
	s_waitcnt lgkmcnt(0)
	s_setprio 1
	s_waitcnt lgkmcnt(0)
	v_mfma_f32_16x16x32_bf16 v[62:65], v[130:133], v[186:189], v[62:65]
	v_mfma_f32_16x16x32_bf16 v[58:61], v[138:141], v[186:189], v[58:61]
	v_mfma_f32_16x16x32_bf16 v[54:57], v[130:133], v[212:215], v[54:57]
	v_mfma_f32_16x16x32_bf16 v[50:53], v[138:141], v[212:215], v[50:53]
	s_barrier
	v_mfma_f32_16x16x32_bf16 v[46:49], v[130:133], v[220:223], v[46:49]
	v_mfma_f32_16x16x32_bf16 v[42:45], v[138:141], v[220:223], v[42:45]
	v_mfma_f32_16x16x32_bf16 v[38:41], v[130:133], v[228:231], v[38:41]
	v_mfma_f32_16x16x32_bf16 v[34:37], v[138:141], v[228:231], v[34:37]
	v_mfma_f32_16x16x32_bf16 v[62:65], v[134:137], v[208:211], v[62:65]
	v_mfma_f32_16x16x32_bf16 v[58:61], v[142:145], v[208:211], v[58:61]
	v_mfma_f32_16x16x32_bf16 v[54:57], v[134:137], v[216:219], v[54:57]
	v_mfma_f32_16x16x32_bf16 v[50:53], v[142:145], v[216:219], v[50:53]
	v_mfma_f32_16x16x32_bf16 v[46:49], v[134:137], v[224:227], v[46:49]
	v_mfma_f32_16x16x32_bf16 v[42:45], v[142:145], v[224:227], v[42:45]
	v_mfma_f32_16x16x32_bf16 v[38:41], v[134:137], v[232:235], v[38:41]
	v_mfma_f32_16x16x32_bf16 v[34:37], v[142:145], v[232:235], v[34:37]
	s_setprio 0
	s_setprio 1
	v_mfma_f32_16x16x32_bf16 v[30:33], v[146:149], v[186:189], v[30:33]
	v_mfma_f32_16x16x32_bf16 v[26:29], v[178:181], v[186:189], v[26:29]
	v_mfma_f32_16x16x32_bf16 v[22:25], v[146:149], v[212:215], v[22:25]
	v_mfma_f32_16x16x32_bf16 v[18:21], v[178:181], v[212:215], v[18:21]
	v_mfma_f32_16x16x32_bf16 v[14:17], v[146:149], v[220:223], v[14:17]
	v_mfma_f32_16x16x32_bf16 v[10:13], v[178:181], v[220:223], v[10:13]
	v_mfma_f32_16x16x32_bf16 v[6:9], v[146:149], v[228:231], v[6:9]
	v_mfma_f32_16x16x32_bf16 v[2:5], v[178:181], v[228:231], v[2:5]
	v_mfma_f32_16x16x32_bf16 v[30:33], v[150:153], v[208:211], v[30:33]
	v_mfma_f32_16x16x32_bf16 v[26:29], v[182:185], v[208:211], v[26:29]
	v_mfma_f32_16x16x32_bf16 v[22:25], v[150:153], v[216:219], v[22:25]
	v_mfma_f32_16x16x32_bf16 v[18:21], v[182:185], v[216:219], v[18:21]
	v_mfma_f32_16x16x32_bf16 v[14:17], v[150:153], v[224:227], v[14:17]
	v_mfma_f32_16x16x32_bf16 v[10:13], v[182:185], v[224:227], v[10:13]
	v_mfma_f32_16x16x32_bf16 v[6:9], v[150:153], v[232:235], v[6:9]
	v_mfma_f32_16x16x32_bf16 v[2:5], v[182:185], v[232:235], v[2:5]
	s_setprio 0
	s_add_u32 s72, s72, 0x100
	s_addc_u32 s73, s73, 0
	s_add_u32 s91, s91, 0x100
	s_addc_u32 s92, s92, 0
	s_barrier
	s_cmp_ge_u32 s93, s84
	s_mov_b32 s60, s93
	s_cbranch_scc0 .LBB0_819
	s_and_b64 vcc, exec, s[18:19]
	s_cbranch_vccz .LBB0_822
	s_barrier

.LBB0_903:
	s_add_u32 s46, s66, 0xfff80080
	s_addc_u32 s47, s67, -1
	s_add_i32 s48, 0, 0x10000
	s_cmp_eq_u32 s84, 28
	s_cselect_b32 s69, s17, s47
	s_cselect_b32 s68, s64, s46
	s_cselect_b32 s61, s13, s83
	s_cselect_b32 s60, s81, s82
	s_add_i32 s49, 0, 0x14000
	v_add_u32_e32 v142, s48, v186
	v_add_u32_e32 v164, s49, v186
	ds_read_b128 v[130:133], v142
	ds_read_b128 v[134:137], v142 offset:1024
	ds_read_b128 v[138:141], v142 offset:2048
	ds_read_b128 v[142:145], v142 offset:3072
	ds_read_b128 v[146:149], v164
	ds_read_b128 v[160:163], v164 offset:1024
	ds_read_b128 v[178:181], v164 offset:2048
	ds_read_b128 v[182:185], v164 offset:3072
	v_lshl_add_u64 v[164:165], s[66:67], 0, v[156:157]
	s_add_i32 m0, s74, 0xc000
	ds_read_b128 v[206:209], v188
	ds_read_b128 v[210:213], v188 offset:1024
	ds_read_b128 v[214:217], v188 offset:2048
	ds_read_b128 v[218:221], v188 offset:3072
	ds_read_b128 v[222:225], v188 offset:4096
	ds_read_b128 v[226:229], v188 offset:5120
	ds_read_b128 v[230:233], v188 offset:6144
	ds_read_b128 v[234:237], v188 offset:7168
	global_load_lds_dwordx4 v[164:165], off
	v_lshl_add_u64 v[164:165], s[66:67], 0, v[158:159]
	s_add_i32 m0, s74, 0xe000
	s_nop 0
	global_load_lds_dwordx4 v[164:165], off
	s_waitcnt vmcnt(8)
	s_waitcnt lgkmcnt(0)
	s_setprio 1
	s_waitcnt lgkmcnt(0)
	v_mfma_f32_16x16x32_bf16 v[126:129], v[130:133], v[206:209], v[126:129]
	v_mfma_f32_16x16x32_bf16 v[122:125], v[138:141], v[206:209], v[122:125]
	v_mfma_f32_16x16x32_bf16 v[118:121], v[130:133], v[214:217], v[118:121]
	v_mfma_f32_16x16x32_bf16 v[110:113], v[138:141], v[214:217], v[110:113]
	s_barrier
	v_mfma_f32_16x16x32_bf16 v[94:97], v[130:133], v[222:225], v[94:97]
	v_mfma_f32_16x16x32_bf16 v[90:93], v[138:141], v[222:225], v[90:93]
	v_mfma_f32_16x16x32_bf16 v[82:85], v[130:133], v[230:233], v[82:85]
	v_mfma_f32_16x16x32_bf16 v[74:77], v[138:141], v[230:233], v[74:77]
	v_mfma_f32_16x16x32_bf16 v[126:129], v[134:137], v[210:213], v[126:129]
	v_mfma_f32_16x16x32_bf16 v[122:125], v[142:145], v[210:213], v[122:125]
	v_mfma_f32_16x16x32_bf16 v[118:121], v[134:137], v[218:221], v[118:121]
	v_mfma_f32_16x16x32_bf16 v[110:113], v[142:145], v[218:221], v[110:113]
	v_mfma_f32_16x16x32_bf16 v[94:97], v[134:137], v[226:229], v[94:97]
	v_mfma_f32_16x16x32_bf16 v[90:93], v[142:145], v[226:229], v[90:93]
	v_mfma_f32_16x16x32_bf16 v[82:85], v[134:137], v[234:237], v[82:85]
	v_mfma_f32_16x16x32_bf16 v[74:77], v[142:145], v[234:237], v[74:77]
	s_setprio 0
	s_setprio 1
	v_mfma_f32_16x16x32_bf16 v[114:117], v[146:149], v[206:209], v[114:117]
	v_mfma_f32_16x16x32_bf16 v[106:109], v[178:181], v[206:209], v[106:109]
	v_mfma_f32_16x16x32_bf16 v[102:105], v[146:149], v[214:217], v[102:105]
	v_mfma_f32_16x16x32_bf16 v[98:101], v[178:181], v[214:217], v[98:101]
	v_mfma_f32_16x16x32_bf16 v[86:89], v[146:149], v[222:225], v[86:89]
	v_mfma_f32_16x16x32_bf16 v[78:81], v[178:181], v[222:225], v[78:81]
	v_mfma_f32_16x16x32_bf16 v[70:73], v[146:149], v[230:233], v[70:73]
	v_mfma_f32_16x16x32_bf16 v[66:69], v[178:181], v[230:233], v[66:69]
	v_mfma_f32_16x16x32_bf16 v[114:117], v[160:163], v[210:213], v[114:117]
	v_mfma_f32_16x16x32_bf16 v[106:109], v[182:185], v[210:213], v[106:109]
	v_mfma_f32_16x16x32_bf16 v[102:105], v[160:163], v[218:221], v[102:105]
	v_mfma_f32_16x16x32_bf16 v[98:101], v[182:185], v[218:221], v[98:101]
	v_mfma_f32_16x16x32_bf16 v[86:89], v[160:163], v[226:229], v[86:89]
	v_mfma_f32_16x16x32_bf16 v[78:81], v[182:185], v[226:229], v[78:81]
	v_mfma_f32_16x16x32_bf16 v[70:73], v[160:163], v[234:237], v[70:73]
	v_mfma_f32_16x16x32_bf16 v[66:69], v[182:185], v[234:237], v[66:69]
	s_setprio 0
	s_add_i32 s46, s48, s73
	v_lshl_add_u64 v[164:165], s[60:61], 0, v[166:167]
	s_mov_b32 m0, s46
	s_barrier
	ds_read_b128 v[206:209], v188 offset:16384
	ds_read_b128 v[210:213], v188 offset:17408
	ds_read_b128 v[214:217], v188 offset:18432
	ds_read_b128 v[218:221], v188 offset:19456
	ds_read_b128 v[222:225], v188 offset:20480
	ds_read_b128 v[226:229], v188 offset:21504
	ds_read_b128 v[230:233], v188 offset:22528
	ds_read_b128 v[234:237], v188 offset:23552
	global_load_lds_dwordx4 v[164:165], off
	s_add_i32 m0, s46, 0x2000
	s_add_u32 s46, s60, 0x80000
	v_lshl_add_u64 v[242:243], s[60:61], 0, v[154:155]
	s_addc_u32 s47, s61, 0
	s_add_i32 s48, s49, s73
	global_load_lds_dwordx4 v[242:243], off
	v_lshl_add_u64 v[244:245], s[46:47], 0, v[166:167]
	s_mov_b32 m0, s48
	v_lshl_add_u64 v[246:247], s[68:69], 0, v[152:153]
	global_load_lds_dwordx4 v[244:245], off
	v_lshl_add_u64 v[244:245], s[46:47], 0, v[154:155]
	s_add_i32 m0, s48, 0x2000
	s_nop 0
	global_load_lds_dwordx4 v[244:245], off
	v_lshl_add_u64 v[244:245], s[68:69], 0, v[150:151]
	s_mov_b32 m0, s74
	s_nop 0
	global_load_lds_dwordx4 v[244:245], off
	s_mov_b32 m0, s75
	s_nop 0
	global_load_lds_dwordx4 v[246:247], off
	s_waitcnt vmcnt(8)
	s_waitcnt lgkmcnt(0)
	s_setprio 1
	s_waitcnt lgkmcnt(0)
	v_mfma_f32_16x16x32_bf16 v[62:65], v[130:133], v[206:209], v[62:65]
	v_mfma_f32_16x16x32_bf16 v[58:61], v[138:141], v[206:209], v[58:61]
	v_mfma_f32_16x16x32_bf16 v[50:53], v[130:133], v[214:217], v[50:53]
	v_mfma_f32_16x16x32_bf16 v[42:45], v[138:141], v[214:217], v[42:45]
	s_barrier
	v_mfma_f32_16x16x32_bf16 v[34:37], v[130:133], v[222:225], v[34:37]
	v_mfma_f32_16x16x32_bf16 v[26:29], v[138:141], v[222:225], v[26:29]
	v_mfma_f32_16x16x32_bf16 v[18:21], v[130:133], v[230:233], v[18:21]
	v_mfma_f32_16x16x32_bf16 v[10:13], v[138:141], v[230:233], v[10:13]
	v_mfma_f32_16x16x32_bf16 v[62:65], v[134:137], v[210:213], v[62:65]
	v_mfma_f32_16x16x32_bf16 v[58:61], v[142:145], v[210:213], v[58:61]
	v_mfma_f32_16x16x32_bf16 v[50:53], v[134:137], v[218:221], v[50:53]
	v_mfma_f32_16x16x32_bf16 v[42:45], v[142:145], v[218:221], v[42:45]
	v_mfma_f32_16x16x32_bf16 v[34:37], v[134:137], v[226:229], v[34:37]
	v_mfma_f32_16x16x32_bf16 v[26:29], v[142:145], v[226:229], v[26:29]
	v_mfma_f32_16x16x32_bf16 v[18:21], v[134:137], v[234:237], v[18:21]
	v_mfma_f32_16x16x32_bf16 v[10:13], v[142:145], v[234:237], v[10:13]
	s_setprio 0
	s_setprio 1
	v_mfma_f32_16x16x32_bf16 v[54:57], v[146:149], v[206:209], v[54:57]
	v_mfma_f32_16x16x32_bf16 v[46:49], v[178:181], v[206:209], v[46:49]
	v_mfma_f32_16x16x32_bf16 v[38:41], v[146:149], v[214:217], v[38:41]
	v_mfma_f32_16x16x32_bf16 v[30:33], v[178:181], v[214:217], v[30:33]
	v_mfma_f32_16x16x32_bf16 v[22:25], v[146:149], v[222:225], v[22:25]
	v_mfma_f32_16x16x32_bf16 v[14:17], v[178:181], v[222:225], v[14:17]
	v_mfma_f32_16x16x32_bf16 v[6:9], v[146:149], v[230:233], v[6:9]
	v_mfma_f32_16x16x32_bf16 v[2:5], v[178:181], v[230:233], v[2:5]
	v_mfma_f32_16x16x32_bf16 v[54:57], v[160:163], v[210:213], v[54:57]
	v_mfma_f32_16x16x32_bf16 v[46:49], v[182:185], v[210:213], v[46:49]
	v_mfma_f32_16x16x32_bf16 v[38:41], v[160:163], v[218:221], v[38:41]
	v_mfma_f32_16x16x32_bf16 v[30:33], v[182:185], v[218:221], v[30:33]
	v_mfma_f32_16x16x32_bf16 v[22:25], v[160:163], v[226:229], v[22:25]
	v_mfma_f32_16x16x32_bf16 v[14:17], v[182:185], v[226:229], v[14:17]
	v_mfma_f32_16x16x32_bf16 v[6:9], v[160:163], v[234:237], v[6:9]
	v_mfma_f32_16x16x32_bf16 v[2:5], v[182:185], v[234:237], v[2:5]
	s_setprio 0
	s_add_i32 s48, 0, 0x18000
	s_add_i32 s49, 0, 0x1c000
	v_add_u32_e32 v142, s48, v186
	v_add_u32_e32 v182, s49, v186
	s_barrier
	ds_read_b128 v[130:133], v142
	ds_read_b128 v[134:137], v142 offset:1024
	ds_read_b128 v[138:141], v142 offset:2048
	ds_read_b128 v[142:145], v142 offset:3072
	ds_read_b128 v[146:149], v182
	ds_read_b128 v[160:163], v182 offset:1024
	ds_read_b128 v[178:181], v182 offset:2048
	ds_read_b128 v[182:185], v182 offset:3072
	s_add_u32 s46, s68, 0x80000
	s_addc_u32 s47, s69, 0
	s_mov_b32 m0, s76
	v_lshl_add_u64 v[248:249], s[46:47], 0, v[150:151]
	ds_read_b128 v[206:209], v188 offset:32768
	ds_read_b128 v[210:213], v188 offset:33792
	ds_read_b128 v[214:217], v188 offset:34816
	ds_read_b128 v[218:221], v188 offset:35840
	ds_read_b128 v[222:225], v188 offset:36864
	ds_read_b128 v[226:229], v188 offset:37888
	ds_read_b128 v[230:233], v188 offset:38912
	ds_read_b128 v[234:237], v188 offset:39936
	global_load_lds_dwordx4 v[248:249], off
	v_lshl_add_u64 v[248:249], s[46:47], 0, v[152:153]
	s_mov_b32 m0, s77
	s_nop 0
	global_load_lds_dwordx4 v[248:249], off
	s_waitcnt vmcnt(8)
	s_waitcnt lgkmcnt(0)
	s_setprio 1
	s_waitcnt lgkmcnt(0)
	v_mfma_f32_16x16x32_bf16 v[126:129], v[130:133], v[206:209], v[126:129]
	v_mfma_f32_16x16x32_bf16 v[122:125], v[138:141], v[206:209], v[122:125]
	v_mfma_f32_16x16x32_bf16 v[118:121], v[130:133], v[214:217], v[118:121]
	v_mfma_f32_16x16x32_bf16 v[110:113], v[138:141], v[214:217], v[110:113]
	s_barrier
	v_mfma_f32_16x16x32_bf16 v[94:97], v[130:133], v[222:225], v[94:97]
	v_mfma_f32_16x16x32_bf16 v[90:93], v[138:141], v[222:225], v[90:93]
	v_mfma_f32_16x16x32_bf16 v[82:85], v[130:133], v[230:233], v[82:85]
	v_mfma_f32_16x16x32_bf16 v[74:77], v[138:141], v[230:233], v[74:77]
	v_mfma_f32_16x16x32_bf16 v[126:129], v[134:137], v[210:213], v[126:129]
	v_mfma_f32_16x16x32_bf16 v[122:125], v[142:145], v[210:213], v[122:125]
	v_mfma_f32_16x16x32_bf16 v[118:121], v[134:137], v[218:221], v[118:121]
	v_mfma_f32_16x16x32_bf16 v[110:113], v[142:145], v[218:221], v[110:113]
	v_mfma_f32_16x16x32_bf16 v[94:97], v[134:137], v[226:229], v[94:97]
	v_mfma_f32_16x16x32_bf16 v[90:93], v[142:145], v[226:229], v[90:93]
	v_mfma_f32_16x16x32_bf16 v[82:85], v[134:137], v[234:237], v[82:85]
	v_mfma_f32_16x16x32_bf16 v[74:77], v[142:145], v[234:237], v[74:77]
	s_setprio 0
	s_setprio 1
	v_mfma_f32_16x16x32_bf16 v[114:117], v[146:149], v[206:209], v[114:117]
	v_mfma_f32_16x16x32_bf16 v[106:109], v[178:181], v[206:209], v[106:109]
	v_mfma_f32_16x16x32_bf16 v[102:105], v[146:149], v[214:217], v[102:105]
	v_mfma_f32_16x16x32_bf16 v[98:101], v[178:181], v[214:217], v[98:101]
	v_mfma_f32_16x16x32_bf16 v[86:89], v[146:149], v[222:225], v[86:89]
	v_mfma_f32_16x16x32_bf16 v[78:81], v[178:181], v[222:225], v[78:81]
	v_mfma_f32_16x16x32_bf16 v[70:73], v[146:149], v[230:233], v[70:73]
	v_mfma_f32_16x16x32_bf16 v[66:69], v[178:181], v[230:233], v[66:69]
	v_mfma_f32_16x16x32_bf16 v[114:117], v[160:163], v[210:213], v[114:117]
	v_mfma_f32_16x16x32_bf16 v[106:109], v[182:185], v[210:213], v[106:109]
	v_mfma_f32_16x16x32_bf16 v[102:105], v[160:163], v[218:221], v[102:105]
	v_mfma_f32_16x16x32_bf16 v[98:101], v[182:185], v[218:221], v[98:101]
	v_mfma_f32_16x16x32_bf16 v[86:89], v[160:163], v[226:229], v[86:89]
	v_mfma_f32_16x16x32_bf16 v[78:81], v[182:185], v[226:229], v[78:81]
	v_mfma_f32_16x16x32_bf16 v[70:73], v[160:163], v[234:237], v[70:73]
	v_mfma_f32_16x16x32_bf16 v[66:69], v[182:185], v[234:237], v[66:69]
	s_setprio 0
	s_add_i32 s46, s48, s73
	v_lshl_add_u64 v[164:165], v[164:165], 0, s[42:43]
	s_mov_b32 m0, s46
	s_barrier
	ds_read_b128 v[206:209], v188 offset:49152
	ds_read_b128 v[210:213], v188 offset:50176
	ds_read_b128 v[214:217], v188 offset:51200
	ds_read_b128 v[218:221], v188 offset:52224
	ds_read_b128 v[222:225], v188 offset:53248
	ds_read_b128 v[226:229], v188 offset:54272
	ds_read_b128 v[230:233], v188 offset:55296
	ds_read_b128 v[234:237], v188 offset:56320
	global_load_lds_dwordx4 v[164:165], off
	s_add_i32 m0, s46, 0x2000
	s_add_u32 s46, s60, 0x80080
	v_lshl_add_u64 v[164:165], v[242:243], 0, s[42:43]
	s_addc_u32 s47, s61, 0
	s_add_i32 s48, s49, s73
	global_load_lds_dwordx4 v[164:165], off
	v_lshl_add_u64 v[164:165], s[46:47], 0, v[166:167]
	s_mov_b32 m0, s48
	s_nop 0
	global_load_lds_dwordx4 v[164:165], off
	v_lshl_add_u64 v[164:165], s[46:47], 0, v[154:155]
	s_add_i32 m0, s48, 0x2000
	s_nop 0
	global_load_lds_dwordx4 v[164:165], off
	v_lshl_add_u64 v[164:165], v[244:245], 0, s[42:43]
	s_mov_b32 m0, s78
	s_nop 0
	global_load_lds_dwordx4 v[164:165], off
	v_lshl_add_u64 v[164:165], v[246:247], 0, s[42:43]
	s_mov_b32 m0, s79
	s_nop 0
	global_load_lds_dwordx4 v[164:165], off
	s_waitcnt vmcnt(8)
	s_waitcnt lgkmcnt(0)
	s_setprio 1
	s_waitcnt lgkmcnt(0)
	v_mfma_f32_16x16x32_bf16 v[62:65], v[130:133], v[206:209], v[62:65]
	v_mfma_f32_16x16x32_bf16 v[58:61], v[138:141], v[206:209], v[58:61]
	v_mfma_f32_16x16x32_bf16 v[50:53], v[130:133], v[214:217], v[50:53]
	v_mfma_f32_16x16x32_bf16 v[42:45], v[138:141], v[214:217], v[42:45]
	s_barrier
	v_mfma_f32_16x16x32_bf16 v[34:37], v[130:133], v[222:225], v[34:37]
	v_mfma_f32_16x16x32_bf16 v[26:29], v[138:141], v[222:225], v[26:29]
	v_mfma_f32_16x16x32_bf16 v[18:21], v[130:133], v[230:233], v[18:21]
	v_mfma_f32_16x16x32_bf16 v[10:13], v[138:141], v[230:233], v[10:13]
	v_mfma_f32_16x16x32_bf16 v[62:65], v[134:137], v[210:213], v[62:65]
	v_mfma_f32_16x16x32_bf16 v[58:61], v[142:145], v[210:213], v[58:61]
	v_mfma_f32_16x16x32_bf16 v[50:53], v[134:137], v[218:221], v[50:53]
	v_mfma_f32_16x16x32_bf16 v[42:45], v[142:145], v[218:221], v[42:45]
	v_mfma_f32_16x16x32_bf16 v[34:37], v[134:137], v[226:229], v[34:37]
	v_mfma_f32_16x16x32_bf16 v[26:29], v[142:145], v[226:229], v[26:29]
	v_mfma_f32_16x16x32_bf16 v[18:21], v[134:137], v[234:237], v[18:21]
	v_mfma_f32_16x16x32_bf16 v[10:13], v[142:145], v[234:237], v[10:13]
	s_setprio 0
	s_setprio 1
	v_mfma_f32_16x16x32_bf16 v[54:57], v[146:149], v[206:209], v[54:57]
	v_mfma_f32_16x16x32_bf16 v[46:49], v[178:181], v[206:209], v[46:49]
	v_mfma_f32_16x16x32_bf16 v[38:41], v[146:149], v[214:217], v[38:41]
	v_mfma_f32_16x16x32_bf16 v[30:33], v[178:181], v[214:217], v[30:33]
	v_mfma_f32_16x16x32_bf16 v[22:25], v[146:149], v[222:225], v[22:25]
	v_mfma_f32_16x16x32_bf16 v[14:17], v[178:181], v[222:225], v[14:17]
	v_mfma_f32_16x16x32_bf16 v[6:9], v[146:149], v[230:233], v[6:9]
	v_mfma_f32_16x16x32_bf16 v[2:5], v[178:181], v[230:233], v[2:5]
	v_mfma_f32_16x16x32_bf16 v[54:57], v[160:163], v[210:213], v[54:57]
	v_mfma_f32_16x16x32_bf16 v[46:49], v[182:185], v[210:213], v[46:49]
	v_mfma_f32_16x16x32_bf16 v[38:41], v[160:163], v[218:221], v[38:41]
	v_mfma_f32_16x16x32_bf16 v[30:33], v[182:185], v[218:221], v[30:33]
	v_mfma_f32_16x16x32_bf16 v[22:25], v[160:163], v[226:229], v[22:25]
	v_mfma_f32_16x16x32_bf16 v[14:17], v[182:185], v[226:229], v[14:17]
	v_mfma_f32_16x16x32_bf16 v[6:9], v[160:163], v[234:237], v[6:9]
	v_mfma_f32_16x16x32_bf16 v[2:5], v[182:185], v[234:237], v[2:5]
	s_setprio 0
	s_add_i32 s84, s84, 2
	s_add_u32 s66, s66, 0x100
	s_addc_u32 s67, s67, 0
	s_add_u32 s82, s82, 0x100
	s_addc_u32 s83, s83, 0
	s_cmp_gt_u32 s84, 29
	s_barrier
	s_cbranch_scc0 .LBB0_903
	s_and_b64 vcc, exec, s[10:11]
	s_cbranch_vccz .LBB0_906
	s_barrier

.LBB0_1035:
	s_add_u32 s46, s64, 0xfff80080
	s_addc_u32 s47, s65, -1
	s_add_i32 s48, 0, 0x10000
	s_cmp_eq_u32 s84, 28
	s_cselect_b32 s67, s17, s47
	s_cselect_b32 s66, s80, s46
	v_add_u32_e32 v140, s48, v142
	s_cselect_b32 s61, s13, s83
	s_cselect_b32 s60, s81, s82
	s_add_i32 s49, 0, 0x14000
	ds_read_b128 v[146:149], v140
	ds_read_b128 v[150:153], v140 offset:1024
	ds_read_b128 v[154:157], v140 offset:2048
	ds_read_b128 v[158:161], v140 offset:3072
	v_add_u32_e32 v140, s49, v142
	ds_read_b128 v[162:165], v140
	ds_read_b128 v[178:181], v140 offset:1024
	ds_read_b128 v[182:185], v140 offset:2048
	ds_read_b128 v[186:189], v140 offset:3072
	v_lshl_add_u64 v[140:141], s[64:65], 0, v[136:137]
	s_add_i32 m0, s23, 0xc000
	ds_read_b128 v[206:209], v144
	ds_read_b128 v[210:213], v144 offset:1024
	ds_read_b128 v[214:217], v144 offset:2048
	ds_read_b128 v[218:221], v144 offset:3072
	ds_read_b128 v[222:225], v144 offset:4096
	ds_read_b128 v[226:229], v144 offset:5120
	ds_read_b128 v[230:233], v144 offset:6144
	ds_read_b128 v[234:237], v144 offset:7168
	global_load_lds_dwordx4 v[140:141], off
	v_lshl_add_u64 v[140:141], s[64:65], 0, v[138:139]
	s_add_i32 m0, s23, 0xe000
	s_nop 0
	global_load_lds_dwordx4 v[140:141], off
	s_waitcnt vmcnt(8)
	s_waitcnt lgkmcnt(0)
	s_setprio 1
	s_waitcnt lgkmcnt(0)
	v_mfma_f32_16x16x32_bf16 v[126:129], v[146:149], v[206:209], v[126:129]
	v_mfma_f32_16x16x32_bf16 v[122:125], v[154:157], v[206:209], v[122:125]
	v_mfma_f32_16x16x32_bf16 v[110:113], v[146:149], v[214:217], v[110:113]
	v_mfma_f32_16x16x32_bf16 v[106:109], v[154:157], v[214:217], v[106:109]
	s_barrier
	v_mfma_f32_16x16x32_bf16 v[94:97], v[146:149], v[222:225], v[94:97]
	v_mfma_f32_16x16x32_bf16 v[90:93], v[154:157], v[222:225], v[90:93]
	v_mfma_f32_16x16x32_bf16 v[78:81], v[146:149], v[230:233], v[78:81]
	v_mfma_f32_16x16x32_bf16 v[74:77], v[154:157], v[230:233], v[74:77]
	v_mfma_f32_16x16x32_bf16 v[126:129], v[150:153], v[210:213], v[126:129]
	v_mfma_f32_16x16x32_bf16 v[122:125], v[158:161], v[210:213], v[122:125]
	v_mfma_f32_16x16x32_bf16 v[110:113], v[150:153], v[218:221], v[110:113]
	v_mfma_f32_16x16x32_bf16 v[106:109], v[158:161], v[218:221], v[106:109]
	v_mfma_f32_16x16x32_bf16 v[94:97], v[150:153], v[226:229], v[94:97]
	v_mfma_f32_16x16x32_bf16 v[90:93], v[158:161], v[226:229], v[90:93]
	v_mfma_f32_16x16x32_bf16 v[78:81], v[150:153], v[234:237], v[78:81]
	v_mfma_f32_16x16x32_bf16 v[74:77], v[158:161], v[234:237], v[74:77]
	s_setprio 0
	s_setprio 1
	v_mfma_f32_16x16x32_bf16 v[118:121], v[162:165], v[206:209], v[118:121]
	v_mfma_f32_16x16x32_bf16 v[114:117], v[182:185], v[206:209], v[114:117]
	v_mfma_f32_16x16x32_bf16 v[102:105], v[162:165], v[214:217], v[102:105]
	v_mfma_f32_16x16x32_bf16 v[98:101], v[182:185], v[214:217], v[98:101]
	v_mfma_f32_16x16x32_bf16 v[86:89], v[162:165], v[222:225], v[86:89]
	v_mfma_f32_16x16x32_bf16 v[82:85], v[182:185], v[222:225], v[82:85]
	v_mfma_f32_16x16x32_bf16 v[70:73], v[162:165], v[230:233], v[70:73]
	v_mfma_f32_16x16x32_bf16 v[66:69], v[182:185], v[230:233], v[66:69]
	v_mfma_f32_16x16x32_bf16 v[118:121], v[178:181], v[210:213], v[118:121]
	v_mfma_f32_16x16x32_bf16 v[114:117], v[186:189], v[210:213], v[114:117]
	v_mfma_f32_16x16x32_bf16 v[102:105], v[178:181], v[218:221], v[102:105]
	v_mfma_f32_16x16x32_bf16 v[98:101], v[186:189], v[218:221], v[98:101]
	v_mfma_f32_16x16x32_bf16 v[86:89], v[178:181], v[226:229], v[86:89]
	v_mfma_f32_16x16x32_bf16 v[82:85], v[186:189], v[226:229], v[82:85]
	v_mfma_f32_16x16x32_bf16 v[70:73], v[178:181], v[234:237], v[70:73]
	v_mfma_f32_16x16x32_bf16 v[66:69], v[186:189], v[234:237], v[66:69]
	s_setprio 0
	s_add_i32 s46, s48, s72
	v_lshl_add_u64 v[140:141], s[60:61], 0, v[166:167]
	s_mov_b32 m0, s46
	s_barrier
	ds_read_b128 v[206:209], v144 offset:16384
	ds_read_b128 v[210:213], v144 offset:17408
	ds_read_b128 v[214:217], v144 offset:18432
	ds_read_b128 v[218:221], v144 offset:19456
	ds_read_b128 v[222:225], v144 offset:20480
	ds_read_b128 v[226:229], v144 offset:21504
	ds_read_b128 v[230:233], v144 offset:22528
	ds_read_b128 v[234:237], v144 offset:23552
	global_load_lds_dwordx4 v[140:141], off
	s_add_i32 m0, s46, 0x2000
	s_add_u32 s46, s60, 0x80000
	v_lshl_add_u64 v[242:243], s[60:61], 0, v[134:135]
	s_addc_u32 s47, s61, 0
	s_add_i32 s48, s49, s72
	global_load_lds_dwordx4 v[242:243], off
	v_lshl_add_u64 v[244:245], s[46:47], 0, v[166:167]
	s_mov_b32 m0, s48
	v_lshl_add_u64 v[246:247], s[66:67], 0, v[132:133]
	global_load_lds_dwordx4 v[244:245], off
	v_lshl_add_u64 v[244:245], s[46:47], 0, v[134:135]
	s_add_i32 m0, s48, 0x2000
	s_nop 0
	global_load_lds_dwordx4 v[244:245], off
	v_lshl_add_u64 v[244:245], s[66:67], 0, v[130:131]
	s_mov_b32 m0, s23
	s_nop 0
	global_load_lds_dwordx4 v[244:245], off
	s_mov_b32 m0, s73
	s_nop 0
	global_load_lds_dwordx4 v[246:247], off
	s_waitcnt vmcnt(8)
	s_waitcnt lgkmcnt(0)
	s_setprio 1
	s_waitcnt lgkmcnt(0)
	v_mfma_f32_16x16x32_bf16 v[62:65], v[146:149], v[206:209], v[62:65]
	v_mfma_f32_16x16x32_bf16 v[58:61], v[154:157], v[206:209], v[58:61]
	v_mfma_f32_16x16x32_bf16 v[46:49], v[146:149], v[214:217], v[46:49]
	v_mfma_f32_16x16x32_bf16 v[42:45], v[154:157], v[214:217], v[42:45]
	s_barrier
	v_mfma_f32_16x16x32_bf16 v[30:33], v[146:149], v[222:225], v[30:33]
	v_mfma_f32_16x16x32_bf16 v[26:29], v[154:157], v[222:225], v[26:29]
	v_mfma_f32_16x16x32_bf16 v[14:17], v[146:149], v[230:233], v[14:17]
	v_mfma_f32_16x16x32_bf16 v[10:13], v[154:157], v[230:233], v[10:13]
	v_mfma_f32_16x16x32_bf16 v[62:65], v[150:153], v[210:213], v[62:65]
	v_mfma_f32_16x16x32_bf16 v[58:61], v[158:161], v[210:213], v[58:61]
	v_mfma_f32_16x16x32_bf16 v[46:49], v[150:153], v[218:221], v[46:49]
	v_mfma_f32_16x16x32_bf16 v[42:45], v[158:161], v[218:221], v[42:45]
	v_mfma_f32_16x16x32_bf16 v[30:33], v[150:153], v[226:229], v[30:33]
	v_mfma_f32_16x16x32_bf16 v[26:29], v[158:161], v[226:229], v[26:29]
	v_mfma_f32_16x16x32_bf16 v[14:17], v[150:153], v[234:237], v[14:17]
	v_mfma_f32_16x16x32_bf16 v[10:13], v[158:161], v[234:237], v[10:13]
	s_setprio 0
	s_setprio 1
	v_mfma_f32_16x16x32_bf16 v[54:57], v[162:165], v[206:209], v[54:57]
	v_mfma_f32_16x16x32_bf16 v[50:53], v[182:185], v[206:209], v[50:53]
	v_mfma_f32_16x16x32_bf16 v[38:41], v[162:165], v[214:217], v[38:41]
	v_mfma_f32_16x16x32_bf16 v[34:37], v[182:185], v[214:217], v[34:37]
	v_mfma_f32_16x16x32_bf16 v[22:25], v[162:165], v[222:225], v[22:25]
	v_mfma_f32_16x16x32_bf16 v[18:21], v[182:185], v[222:225], v[18:21]
	v_mfma_f32_16x16x32_bf16 v[6:9], v[162:165], v[230:233], v[6:9]
	v_mfma_f32_16x16x32_bf16 v[2:5], v[182:185], v[230:233], v[2:5]
	v_mfma_f32_16x16x32_bf16 v[54:57], v[178:181], v[210:213], v[54:57]
	v_mfma_f32_16x16x32_bf16 v[50:53], v[186:189], v[210:213], v[50:53]
	v_mfma_f32_16x16x32_bf16 v[38:41], v[178:181], v[218:221], v[38:41]
	v_mfma_f32_16x16x32_bf16 v[34:37], v[186:189], v[218:221], v[34:37]
	v_mfma_f32_16x16x32_bf16 v[22:25], v[178:181], v[226:229], v[22:25]
	v_mfma_f32_16x16x32_bf16 v[18:21], v[186:189], v[226:229], v[18:21]
	v_mfma_f32_16x16x32_bf16 v[6:9], v[178:181], v[234:237], v[6:9]
	v_mfma_f32_16x16x32_bf16 v[2:5], v[186:189], v[234:237], v[2:5]
	s_setprio 0
	s_add_i32 s48, 0, 0x18000
	v_add_u32_e32 v145, s48, v142
	s_add_i32 s49, 0, 0x1c000
	s_barrier
	ds_read_b128 v[146:149], v145
	ds_read_b128 v[150:153], v145 offset:1024
	ds_read_b128 v[154:157], v145 offset:2048
	ds_read_b128 v[158:161], v145 offset:3072
	v_add_u32_e32 v145, s49, v142
	ds_read_b128 v[162:165], v145
	ds_read_b128 v[178:181], v145 offset:1024
	ds_read_b128 v[182:185], v145 offset:2048
	ds_read_b128 v[186:189], v145 offset:3072
	s_add_u32 s46, s66, 0x80000
	s_addc_u32 s47, s67, 0
	s_mov_b32 m0, s74
	v_lshl_add_u64 v[248:249], s[46:47], 0, v[130:131]
	ds_read_b128 v[206:209], v144 offset:32768
	ds_read_b128 v[210:213], v144 offset:33792
	ds_read_b128 v[214:217], v144 offset:34816
	ds_read_b128 v[218:221], v144 offset:35840
	ds_read_b128 v[222:225], v144 offset:36864
	ds_read_b128 v[226:229], v144 offset:37888
	ds_read_b128 v[230:233], v144 offset:38912
	ds_read_b128 v[234:237], v144 offset:39936
	global_load_lds_dwordx4 v[248:249], off
	v_lshl_add_u64 v[248:249], s[46:47], 0, v[132:133]
	s_mov_b32 m0, s75
	s_nop 0
	global_load_lds_dwordx4 v[248:249], off
	s_waitcnt vmcnt(8)
	s_waitcnt lgkmcnt(0)
	s_setprio 1
	s_waitcnt lgkmcnt(0)
	v_mfma_f32_16x16x32_bf16 v[126:129], v[146:149], v[206:209], v[126:129]
	v_mfma_f32_16x16x32_bf16 v[122:125], v[154:157], v[206:209], v[122:125]
	v_mfma_f32_16x16x32_bf16 v[110:113], v[146:149], v[214:217], v[110:113]
	v_mfma_f32_16x16x32_bf16 v[106:109], v[154:157], v[214:217], v[106:109]
	s_barrier
	v_mfma_f32_16x16x32_bf16 v[94:97], v[146:149], v[222:225], v[94:97]
	v_mfma_f32_16x16x32_bf16 v[90:93], v[154:157], v[222:225], v[90:93]
	v_mfma_f32_16x16x32_bf16 v[78:81], v[146:149], v[230:233], v[78:81]
	v_mfma_f32_16x16x32_bf16 v[74:77], v[154:157], v[230:233], v[74:77]
	v_mfma_f32_16x16x32_bf16 v[126:129], v[150:153], v[210:213], v[126:129]
	v_mfma_f32_16x16x32_bf16 v[122:125], v[158:161], v[210:213], v[122:125]
	v_mfma_f32_16x16x32_bf16 v[110:113], v[150:153], v[218:221], v[110:113]
	v_mfma_f32_16x16x32_bf16 v[106:109], v[158:161], v[218:221], v[106:109]
	v_mfma_f32_16x16x32_bf16 v[94:97], v[150:153], v[226:229], v[94:97]
	v_mfma_f32_16x16x32_bf16 v[90:93], v[158:161], v[226:229], v[90:93]
	v_mfma_f32_16x16x32_bf16 v[78:81], v[150:153], v[234:237], v[78:81]
	v_mfma_f32_16x16x32_bf16 v[74:77], v[158:161], v[234:237], v[74:77]
	s_setprio 0
	s_setprio 1
	v_mfma_f32_16x16x32_bf16 v[118:121], v[162:165], v[206:209], v[118:121]
	v_mfma_f32_16x16x32_bf16 v[114:117], v[182:185], v[206:209], v[114:117]
	v_mfma_f32_16x16x32_bf16 v[102:105], v[162:165], v[214:217], v[102:105]
	v_mfma_f32_16x16x32_bf16 v[98:101], v[182:185], v[214:217], v[98:101]
	v_mfma_f32_16x16x32_bf16 v[86:89], v[162:165], v[222:225], v[86:89]
	v_mfma_f32_16x16x32_bf16 v[82:85], v[182:185], v[222:225], v[82:85]
	v_mfma_f32_16x16x32_bf16 v[70:73], v[162:165], v[230:233], v[70:73]
	v_mfma_f32_16x16x32_bf16 v[66:69], v[182:185], v[230:233], v[66:69]
	v_mfma_f32_16x16x32_bf16 v[118:121], v[178:181], v[210:213], v[118:121]
	v_mfma_f32_16x16x32_bf16 v[114:117], v[186:189], v[210:213], v[114:117]
	v_mfma_f32_16x16x32_bf16 v[102:105], v[178:181], v[218:221], v[102:105]
	v_mfma_f32_16x16x32_bf16 v[98:101], v[186:189], v[218:221], v[98:101]
	v_mfma_f32_16x16x32_bf16 v[86:89], v[178:181], v[226:229], v[86:89]
	v_mfma_f32_16x16x32_bf16 v[82:85], v[186:189], v[226:229], v[82:85]
	v_mfma_f32_16x16x32_bf16 v[70:73], v[178:181], v[234:237], v[70:73]
	v_mfma_f32_16x16x32_bf16 v[66:69], v[186:189], v[234:237], v[66:69]
	s_setprio 0
	s_add_i32 s46, s48, s72
	v_lshl_add_u64 v[140:141], v[140:141], 0, s[42:43]
	s_mov_b32 m0, s46
	s_barrier
	ds_read_b128 v[206:209], v144 offset:49152
	ds_read_b128 v[210:213], v144 offset:50176
	ds_read_b128 v[214:217], v144 offset:51200
	ds_read_b128 v[218:221], v144 offset:52224
	ds_read_b128 v[222:225], v144 offset:53248
	ds_read_b128 v[226:229], v144 offset:54272
	ds_read_b128 v[230:233], v144 offset:55296
	ds_read_b128 v[234:237], v144 offset:56320
	global_load_lds_dwordx4 v[140:141], off
	s_add_i32 m0, s46, 0x2000
	s_add_u32 s46, s60, 0x80080
	v_lshl_add_u64 v[140:141], v[242:243], 0, s[42:43]
	s_addc_u32 s47, s61, 0
	s_add_i32 s48, s49, s72
	global_load_lds_dwordx4 v[140:141], off
	v_lshl_add_u64 v[140:141], s[46:47], 0, v[166:167]
	s_mov_b32 m0, s48
	s_nop 0
	global_load_lds_dwordx4 v[140:141], off
	v_lshl_add_u64 v[140:141], s[46:47], 0, v[134:135]
	s_add_i32 m0, s48, 0x2000
	s_nop 0
	global_load_lds_dwordx4 v[140:141], off
	v_lshl_add_u64 v[140:141], v[244:245], 0, s[42:43]
	s_mov_b32 m0, s76
	s_nop 0
	global_load_lds_dwordx4 v[140:141], off
	v_lshl_add_u64 v[140:141], v[246:247], 0, s[42:43]
	s_mov_b32 m0, s77
	s_nop 0
	global_load_lds_dwordx4 v[140:141], off
	s_waitcnt vmcnt(8)
	s_waitcnt lgkmcnt(0)
	s_setprio 1
	s_waitcnt lgkmcnt(0)
	v_mfma_f32_16x16x32_bf16 v[62:65], v[146:149], v[206:209], v[62:65]
	v_mfma_f32_16x16x32_bf16 v[58:61], v[154:157], v[206:209], v[58:61]
	v_mfma_f32_16x16x32_bf16 v[46:49], v[146:149], v[214:217], v[46:49]
	v_mfma_f32_16x16x32_bf16 v[42:45], v[154:157], v[214:217], v[42:45]
	s_barrier
	v_mfma_f32_16x16x32_bf16 v[30:33], v[146:149], v[222:225], v[30:33]
	v_mfma_f32_16x16x32_bf16 v[26:29], v[154:157], v[222:225], v[26:29]
	v_mfma_f32_16x16x32_bf16 v[14:17], v[146:149], v[230:233], v[14:17]
	v_mfma_f32_16x16x32_bf16 v[10:13], v[154:157], v[230:233], v[10:13]
	v_mfma_f32_16x16x32_bf16 v[62:65], v[150:153], v[210:213], v[62:65]
	v_mfma_f32_16x16x32_bf16 v[58:61], v[158:161], v[210:213], v[58:61]
	v_mfma_f32_16x16x32_bf16 v[46:49], v[150:153], v[218:221], v[46:49]
	v_mfma_f32_16x16x32_bf16 v[42:45], v[158:161], v[218:221], v[42:45]
	v_mfma_f32_16x16x32_bf16 v[30:33], v[150:153], v[226:229], v[30:33]
	v_mfma_f32_16x16x32_bf16 v[26:29], v[158:161], v[226:229], v[26:29]
	v_mfma_f32_16x16x32_bf16 v[14:17], v[150:153], v[234:237], v[14:17]
	v_mfma_f32_16x16x32_bf16 v[10:13], v[158:161], v[234:237], v[10:13]
	s_setprio 0
	s_setprio 1
	v_mfma_f32_16x16x32_bf16 v[54:57], v[162:165], v[206:209], v[54:57]
	v_mfma_f32_16x16x32_bf16 v[50:53], v[182:185], v[206:209], v[50:53]
	v_mfma_f32_16x16x32_bf16 v[38:41], v[162:165], v[214:217], v[38:41]
	v_mfma_f32_16x16x32_bf16 v[34:37], v[182:185], v[214:217], v[34:37]
	v_mfma_f32_16x16x32_bf16 v[22:25], v[162:165], v[222:225], v[22:25]
	v_mfma_f32_16x16x32_bf16 v[18:21], v[182:185], v[222:225], v[18:21]
	v_mfma_f32_16x16x32_bf16 v[6:9], v[162:165], v[230:233], v[6:9]
	v_mfma_f32_16x16x32_bf16 v[2:5], v[182:185], v[230:233], v[2:5]
	v_mfma_f32_16x16x32_bf16 v[54:57], v[178:181], v[210:213], v[54:57]
	v_mfma_f32_16x16x32_bf16 v[50:53], v[186:189], v[210:213], v[50:53]
	v_mfma_f32_16x16x32_bf16 v[38:41], v[178:181], v[218:221], v[38:41]
	v_mfma_f32_16x16x32_bf16 v[34:37], v[186:189], v[218:221], v[34:37]
	v_mfma_f32_16x16x32_bf16 v[22:25], v[178:181], v[226:229], v[22:25]
	v_mfma_f32_16x16x32_bf16 v[18:21], v[186:189], v[226:229], v[18:21]
	v_mfma_f32_16x16x32_bf16 v[6:9], v[178:181], v[234:237], v[6:9]
	v_mfma_f32_16x16x32_bf16 v[2:5], v[186:189], v[234:237], v[2:5]
	s_setprio 0
	s_add_i32 s84, s84, 2
	s_add_u32 s64, s64, 0x100
	s_addc_u32 s65, s65, 0
	s_add_u32 s82, s82, 0x100
	s_addc_u32 s83, s83, 0
	s_cmp_gt_u32 s84, 29
	s_barrier
	s_cbranch_scc0 .LBB0_1035
	s_and_b64 vcc, exec, s[10:11]
	s_cbranch_vccz .LBB0_1038
	s_barrier

.LBB0_1112:
	s_add_u32 s46, s64, 0xffe00080
	s_addc_u32 s47, s65, -1
	s_add_i32 s48, 0, 0x10000
	s_cmpk_eq_i32 s84, 0x7c
	s_cselect_b32 s67, s19, s47
	s_cselect_b32 s66, s80, s46
	s_cselect_b32 s61, s17, s83
	s_cselect_b32 s60, s81, s82
	s_add_i32 s49, 0, 0x14000
	v_add_u32_e32 v142, s48, v182
	v_add_u32_e32 v164, s49, v182
	ds_read_b128 v[130:133], v142
	ds_read_b128 v[134:137], v142 offset:1024
	ds_read_b128 v[138:141], v142 offset:2048
	ds_read_b128 v[142:145], v142 offset:3072
	ds_read_b128 v[146:149], v164
	ds_read_b128 v[160:163], v164 offset:1024
	ds_read_b128 v[178:181], v164 offset:2048
	ds_read_b128 v[186:189], v164 offset:3072
	v_lshl_add_u64 v[164:165], s[64:65], 0, v[156:157]
	s_add_i32 m0, s63, 0xc000
	ds_read_b128 v[206:209], v184
	ds_read_b128 v[210:213], v184 offset:1024
	ds_read_b128 v[214:217], v184 offset:2048
	ds_read_b128 v[218:221], v184 offset:3072
	ds_read_b128 v[222:225], v184 offset:4096
	ds_read_b128 v[226:229], v184 offset:5120
	ds_read_b128 v[230:233], v184 offset:6144
	ds_read_b128 v[234:237], v184 offset:7168
	global_load_lds_dwordx4 v[164:165], off
	v_lshl_add_u64 v[164:165], s[64:65], 0, v[158:159]
	s_add_i32 m0, s63, 0xe000
	s_nop 0
	global_load_lds_dwordx4 v[164:165], off
	s_waitcnt vmcnt(8)
	s_waitcnt lgkmcnt(0)
	s_setprio 1
	s_waitcnt lgkmcnt(0)
	v_mfma_f32_16x16x32_bf16 v[126:129], v[130:133], v[206:209], v[126:129]
	v_mfma_f32_16x16x32_bf16 v[122:125], v[138:141], v[206:209], v[122:125]
	v_mfma_f32_16x16x32_bf16 v[118:121], v[130:133], v[214:217], v[118:121]
	v_mfma_f32_16x16x32_bf16 v[114:117], v[138:141], v[214:217], v[114:117]
	s_barrier
	v_mfma_f32_16x16x32_bf16 v[94:97], v[130:133], v[222:225], v[94:97]
	v_mfma_f32_16x16x32_bf16 v[90:93], v[138:141], v[222:225], v[90:93]
	v_mfma_f32_16x16x32_bf16 v[82:85], v[130:133], v[230:233], v[82:85]
	v_mfma_f32_16x16x32_bf16 v[74:77], v[138:141], v[230:233], v[74:77]
	v_mfma_f32_16x16x32_bf16 v[126:129], v[134:137], v[210:213], v[126:129]
	v_mfma_f32_16x16x32_bf16 v[122:125], v[142:145], v[210:213], v[122:125]
	v_mfma_f32_16x16x32_bf16 v[118:121], v[134:137], v[218:221], v[118:121]
	v_mfma_f32_16x16x32_bf16 v[114:117], v[142:145], v[218:221], v[114:117]
	v_mfma_f32_16x16x32_bf16 v[94:97], v[134:137], v[226:229], v[94:97]
	v_mfma_f32_16x16x32_bf16 v[90:93], v[142:145], v[226:229], v[90:93]
	v_mfma_f32_16x16x32_bf16 v[82:85], v[134:137], v[234:237], v[82:85]
	v_mfma_f32_16x16x32_bf16 v[74:77], v[142:145], v[234:237], v[74:77]
	s_setprio 0
	s_setprio 1
	v_mfma_f32_16x16x32_bf16 v[110:113], v[146:149], v[206:209], v[110:113]
	v_mfma_f32_16x16x32_bf16 v[106:109], v[178:181], v[206:209], v[106:109]
	v_mfma_f32_16x16x32_bf16 v[102:105], v[146:149], v[214:217], v[102:105]
	v_mfma_f32_16x16x32_bf16 v[98:101], v[178:181], v[214:217], v[98:101]
	v_mfma_f32_16x16x32_bf16 v[86:89], v[146:149], v[222:225], v[86:89]
	v_mfma_f32_16x16x32_bf16 v[78:81], v[178:181], v[222:225], v[78:81]
	v_mfma_f32_16x16x32_bf16 v[70:73], v[146:149], v[230:233], v[70:73]
	v_mfma_f32_16x16x32_bf16 v[66:69], v[178:181], v[230:233], v[66:69]
	v_mfma_f32_16x16x32_bf16 v[110:113], v[160:163], v[210:213], v[110:113]
	v_mfma_f32_16x16x32_bf16 v[106:109], v[186:189], v[210:213], v[106:109]
	v_mfma_f32_16x16x32_bf16 v[102:105], v[160:163], v[218:221], v[102:105]
	v_mfma_f32_16x16x32_bf16 v[98:101], v[186:189], v[218:221], v[98:101]
	v_mfma_f32_16x16x32_bf16 v[86:89], v[160:163], v[226:229], v[86:89]
	v_mfma_f32_16x16x32_bf16 v[78:81], v[186:189], v[226:229], v[78:81]
	v_mfma_f32_16x16x32_bf16 v[70:73], v[160:163], v[234:237], v[70:73]
	v_mfma_f32_16x16x32_bf16 v[66:69], v[186:189], v[234:237], v[66:69]
	s_setprio 0
	s_add_i32 s46, s48, s72
	v_lshl_add_u64 v[164:165], s[60:61], 0, v[166:167]
	s_mov_b32 m0, s46
	s_barrier
	ds_read_b128 v[206:209], v184 offset:16384
	ds_read_b128 v[210:213], v184 offset:17408
	ds_read_b128 v[214:217], v184 offset:18432
	ds_read_b128 v[218:221], v184 offset:19456
	ds_read_b128 v[222:225], v184 offset:20480
	ds_read_b128 v[226:229], v184 offset:21504
	ds_read_b128 v[230:233], v184 offset:22528
	ds_read_b128 v[234:237], v184 offset:23552
	global_load_lds_dwordx4 v[164:165], off
	s_add_i32 m0, s46, 0x2000
	s_add_u32 s46, s60, 0x200000
	v_lshl_add_u64 v[242:243], s[60:61], 0, v[154:155]
	s_addc_u32 s47, s61, 0
	s_add_i32 s48, s49, s72
	global_load_lds_dwordx4 v[242:243], off
	v_lshl_add_u64 v[244:245], s[46:47], 0, v[166:167]
	s_mov_b32 m0, s48
	v_lshl_add_u64 v[246:247], s[66:67], 0, v[152:153]
	global_load_lds_dwordx4 v[244:245], off
	v_lshl_add_u64 v[244:245], s[46:47], 0, v[154:155]
	s_add_i32 m0, s48, 0x2000
	s_nop 0
	global_load_lds_dwordx4 v[244:245], off
	v_lshl_add_u64 v[244:245], s[66:67], 0, v[150:151]
	s_mov_b32 m0, s63
	s_nop 0
	global_load_lds_dwordx4 v[244:245], off
	s_mov_b32 m0, s73
	s_nop 0
	global_load_lds_dwordx4 v[246:247], off
	s_waitcnt vmcnt(8)
	s_waitcnt lgkmcnt(0)
	s_setprio 1
	s_waitcnt lgkmcnt(0)
	v_mfma_f32_16x16x32_bf16 v[62:65], v[130:133], v[206:209], v[62:65]
	v_mfma_f32_16x16x32_bf16 v[58:61], v[138:141], v[206:209], v[58:61]
	v_mfma_f32_16x16x32_bf16 v[50:53], v[130:133], v[214:217], v[50:53]
	v_mfma_f32_16x16x32_bf16 v[42:45], v[138:141], v[214:217], v[42:45]
	s_barrier
	v_mfma_f32_16x16x32_bf16 v[34:37], v[130:133], v[222:225], v[34:37]
	v_mfma_f32_16x16x32_bf16 v[26:29], v[138:141], v[222:225], v[26:29]
	v_mfma_f32_16x16x32_bf16 v[18:21], v[130:133], v[230:233], v[18:21]
	v_mfma_f32_16x16x32_bf16 v[10:13], v[138:141], v[230:233], v[10:13]
	v_mfma_f32_16x16x32_bf16 v[62:65], v[134:137], v[210:213], v[62:65]
	v_mfma_f32_16x16x32_bf16 v[58:61], v[142:145], v[210:213], v[58:61]
	v_mfma_f32_16x16x32_bf16 v[50:53], v[134:137], v[218:221], v[50:53]
	v_mfma_f32_16x16x32_bf16 v[42:45], v[142:145], v[218:221], v[42:45]
	v_mfma_f32_16x16x32_bf16 v[34:37], v[134:137], v[226:229], v[34:37]
	v_mfma_f32_16x16x32_bf16 v[26:29], v[142:145], v[226:229], v[26:29]
	v_mfma_f32_16x16x32_bf16 v[18:21], v[134:137], v[234:237], v[18:21]
	v_mfma_f32_16x16x32_bf16 v[10:13], v[142:145], v[234:237], v[10:13]
	s_setprio 0
	s_setprio 1
	v_mfma_f32_16x16x32_bf16 v[54:57], v[146:149], v[206:209], v[54:57]
	v_mfma_f32_16x16x32_bf16 v[46:49], v[178:181], v[206:209], v[46:49]
	v_mfma_f32_16x16x32_bf16 v[38:41], v[146:149], v[214:217], v[38:41]
	v_mfma_f32_16x16x32_bf16 v[30:33], v[178:181], v[214:217], v[30:33]
	v_mfma_f32_16x16x32_bf16 v[22:25], v[146:149], v[222:225], v[22:25]
	v_mfma_f32_16x16x32_bf16 v[14:17], v[178:181], v[222:225], v[14:17]
	v_mfma_f32_16x16x32_bf16 v[6:9], v[146:149], v[230:233], v[6:9]
	v_mfma_f32_16x16x32_bf16 v[2:5], v[178:181], v[230:233], v[2:5]
	v_mfma_f32_16x16x32_bf16 v[54:57], v[160:163], v[210:213], v[54:57]
	v_mfma_f32_16x16x32_bf16 v[46:49], v[186:189], v[210:213], v[46:49]
	v_mfma_f32_16x16x32_bf16 v[38:41], v[160:163], v[218:221], v[38:41]
	v_mfma_f32_16x16x32_bf16 v[30:33], v[186:189], v[218:221], v[30:33]
	v_mfma_f32_16x16x32_bf16 v[22:25], v[160:163], v[226:229], v[22:25]
	v_mfma_f32_16x16x32_bf16 v[14:17], v[186:189], v[226:229], v[14:17]
	v_mfma_f32_16x16x32_bf16 v[6:9], v[160:163], v[234:237], v[6:9]
	v_mfma_f32_16x16x32_bf16 v[2:5], v[186:189], v[234:237], v[2:5]
	s_setprio 0
	s_add_i32 s48, 0, 0x18000
	s_add_i32 s49, 0, 0x1c000
	v_add_u32_e32 v142, s48, v182
	v_add_u32_e32 v185, s49, v182
	s_barrier
	ds_read_b128 v[130:133], v142
	ds_read_b128 v[134:137], v142 offset:1024
	ds_read_b128 v[138:141], v142 offset:2048
	ds_read_b128 v[142:145], v142 offset:3072
	ds_read_b128 v[146:149], v185
	ds_read_b128 v[160:163], v185 offset:1024
	ds_read_b128 v[178:181], v185 offset:2048
	ds_read_b128 v[186:189], v185 offset:3072
	s_add_u32 s46, s66, 0x200000
	s_addc_u32 s47, s67, 0
	s_mov_b32 m0, s74
	v_lshl_add_u64 v[248:249], s[46:47], 0, v[150:151]
	ds_read_b128 v[206:209], v184 offset:32768
	ds_read_b128 v[210:213], v184 offset:33792
	ds_read_b128 v[214:217], v184 offset:34816
	ds_read_b128 v[218:221], v184 offset:35840
	ds_read_b128 v[222:225], v184 offset:36864
	ds_read_b128 v[226:229], v184 offset:37888
	ds_read_b128 v[230:233], v184 offset:38912
	ds_read_b128 v[234:237], v184 offset:39936
	global_load_lds_dwordx4 v[248:249], off
	v_lshl_add_u64 v[248:249], s[46:47], 0, v[152:153]
	s_mov_b32 m0, s75
	s_nop 0
	global_load_lds_dwordx4 v[248:249], off
	s_waitcnt vmcnt(8)
	s_waitcnt lgkmcnt(0)
	s_setprio 1
	s_waitcnt lgkmcnt(0)
	v_mfma_f32_16x16x32_bf16 v[126:129], v[130:133], v[206:209], v[126:129]
	v_mfma_f32_16x16x32_bf16 v[122:125], v[138:141], v[206:209], v[122:125]
	v_mfma_f32_16x16x32_bf16 v[118:121], v[130:133], v[214:217], v[118:121]
	v_mfma_f32_16x16x32_bf16 v[114:117], v[138:141], v[214:217], v[114:117]
	s_barrier
	v_mfma_f32_16x16x32_bf16 v[94:97], v[130:133], v[222:225], v[94:97]
	v_mfma_f32_16x16x32_bf16 v[90:93], v[138:141], v[222:225], v[90:93]
	v_mfma_f32_16x16x32_bf16 v[82:85], v[130:133], v[230:233], v[82:85]
	v_mfma_f32_16x16x32_bf16 v[74:77], v[138:141], v[230:233], v[74:77]
	v_mfma_f32_16x16x32_bf16 v[126:129], v[134:137], v[210:213], v[126:129]
	v_mfma_f32_16x16x32_bf16 v[122:125], v[142:145], v[210:213], v[122:125]
	v_mfma_f32_16x16x32_bf16 v[118:121], v[134:137], v[218:221], v[118:121]
	v_mfma_f32_16x16x32_bf16 v[114:117], v[142:145], v[218:221], v[114:117]
	v_mfma_f32_16x16x32_bf16 v[94:97], v[134:137], v[226:229], v[94:97]
	v_mfma_f32_16x16x32_bf16 v[90:93], v[142:145], v[226:229], v[90:93]
	v_mfma_f32_16x16x32_bf16 v[82:85], v[134:137], v[234:237], v[82:85]
	v_mfma_f32_16x16x32_bf16 v[74:77], v[142:145], v[234:237], v[74:77]
	s_setprio 0
	s_setprio 1
	v_mfma_f32_16x16x32_bf16 v[110:113], v[146:149], v[206:209], v[110:113]
	v_mfma_f32_16x16x32_bf16 v[106:109], v[178:181], v[206:209], v[106:109]
	v_mfma_f32_16x16x32_bf16 v[102:105], v[146:149], v[214:217], v[102:105]
	v_mfma_f32_16x16x32_bf16 v[98:101], v[178:181], v[214:217], v[98:101]
	v_mfma_f32_16x16x32_bf16 v[86:89], v[146:149], v[222:225], v[86:89]
	v_mfma_f32_16x16x32_bf16 v[78:81], v[178:181], v[222:225], v[78:81]
	v_mfma_f32_16x16x32_bf16 v[70:73], v[146:149], v[230:233], v[70:73]
	v_mfma_f32_16x16x32_bf16 v[66:69], v[178:181], v[230:233], v[66:69]
	v_mfma_f32_16x16x32_bf16 v[110:113], v[160:163], v[210:213], v[110:113]
	v_mfma_f32_16x16x32_bf16 v[106:109], v[186:189], v[210:213], v[106:109]
	v_mfma_f32_16x16x32_bf16 v[102:105], v[160:163], v[218:221], v[102:105]
	v_mfma_f32_16x16x32_bf16 v[98:101], v[186:189], v[218:221], v[98:101]
	v_mfma_f32_16x16x32_bf16 v[86:89], v[160:163], v[226:229], v[86:89]
	v_mfma_f32_16x16x32_bf16 v[78:81], v[186:189], v[226:229], v[78:81]
	v_mfma_f32_16x16x32_bf16 v[70:73], v[160:163], v[234:237], v[70:73]
	v_mfma_f32_16x16x32_bf16 v[66:69], v[186:189], v[234:237], v[66:69]
	s_setprio 0
	s_add_i32 s46, s48, s72
	v_lshl_add_u64 v[164:165], v[164:165], 0, s[42:43]
	s_mov_b32 m0, s46
	s_barrier
	ds_read_b128 v[206:209], v184 offset:49152
	ds_read_b128 v[210:213], v184 offset:50176
	ds_read_b128 v[214:217], v184 offset:51200
	ds_read_b128 v[218:221], v184 offset:52224
	ds_read_b128 v[222:225], v184 offset:53248
	ds_read_b128 v[226:229], v184 offset:54272
	ds_read_b128 v[230:233], v184 offset:55296
	ds_read_b128 v[234:237], v184 offset:56320
	global_load_lds_dwordx4 v[164:165], off
	s_add_i32 m0, s46, 0x2000
	s_add_u32 s46, s60, 0x200080
	v_lshl_add_u64 v[164:165], v[242:243], 0, s[42:43]
	s_addc_u32 s47, s61, 0
	s_add_i32 s48, s49, s72
	global_load_lds_dwordx4 v[164:165], off
	v_lshl_add_u64 v[164:165], s[46:47], 0, v[166:167]
	s_mov_b32 m0, s48
	s_nop 0
	global_load_lds_dwordx4 v[164:165], off
	v_lshl_add_u64 v[164:165], s[46:47], 0, v[154:155]
	s_add_i32 m0, s48, 0x2000
	s_nop 0
	global_load_lds_dwordx4 v[164:165], off
	v_lshl_add_u64 v[164:165], v[244:245], 0, s[42:43]
	s_mov_b32 m0, s76
	s_nop 0
	global_load_lds_dwordx4 v[164:165], off
	v_lshl_add_u64 v[164:165], v[246:247], 0, s[42:43]
	s_mov_b32 m0, s77
	s_nop 0
	global_load_lds_dwordx4 v[164:165], off
	s_waitcnt vmcnt(8)
	s_waitcnt lgkmcnt(0)
	s_setprio 1
	s_waitcnt lgkmcnt(0)
	v_mfma_f32_16x16x32_bf16 v[62:65], v[130:133], v[206:209], v[62:65]
	v_mfma_f32_16x16x32_bf16 v[58:61], v[138:141], v[206:209], v[58:61]
	v_mfma_f32_16x16x32_bf16 v[50:53], v[130:133], v[214:217], v[50:53]
	v_mfma_f32_16x16x32_bf16 v[42:45], v[138:141], v[214:217], v[42:45]
	s_barrier
	v_mfma_f32_16x16x32_bf16 v[34:37], v[130:133], v[222:225], v[34:37]
	v_mfma_f32_16x16x32_bf16 v[26:29], v[138:141], v[222:225], v[26:29]
	v_mfma_f32_16x16x32_bf16 v[18:21], v[130:133], v[230:233], v[18:21]
	v_mfma_f32_16x16x32_bf16 v[10:13], v[138:141], v[230:233], v[10:13]
	v_mfma_f32_16x16x32_bf16 v[62:65], v[134:137], v[210:213], v[62:65]
	v_mfma_f32_16x16x32_bf16 v[58:61], v[142:145], v[210:213], v[58:61]
	v_mfma_f32_16x16x32_bf16 v[50:53], v[134:137], v[218:221], v[50:53]
	v_mfma_f32_16x16x32_bf16 v[42:45], v[142:145], v[218:221], v[42:45]
	v_mfma_f32_16x16x32_bf16 v[34:37], v[134:137], v[226:229], v[34:37]
	v_mfma_f32_16x16x32_bf16 v[26:29], v[142:145], v[226:229], v[26:29]
	v_mfma_f32_16x16x32_bf16 v[18:21], v[134:137], v[234:237], v[18:21]
	v_mfma_f32_16x16x32_bf16 v[10:13], v[142:145], v[234:237], v[10:13]
	s_setprio 0
	s_setprio 1
	v_mfma_f32_16x16x32_bf16 v[54:57], v[146:149], v[206:209], v[54:57]
	v_mfma_f32_16x16x32_bf16 v[46:49], v[178:181], v[206:209], v[46:49]
	v_mfma_f32_16x16x32_bf16 v[38:41], v[146:149], v[214:217], v[38:41]
	v_mfma_f32_16x16x32_bf16 v[30:33], v[178:181], v[214:217], v[30:33]
	v_mfma_f32_16x16x32_bf16 v[22:25], v[146:149], v[222:225], v[22:25]
	v_mfma_f32_16x16x32_bf16 v[14:17], v[178:181], v[222:225], v[14:17]
	v_mfma_f32_16x16x32_bf16 v[6:9], v[146:149], v[230:233], v[6:9]
	v_mfma_f32_16x16x32_bf16 v[2:5], v[178:181], v[230:233], v[2:5]
	v_mfma_f32_16x16x32_bf16 v[54:57], v[160:163], v[210:213], v[54:57]
	v_mfma_f32_16x16x32_bf16 v[46:49], v[186:189], v[210:213], v[46:49]
	v_mfma_f32_16x16x32_bf16 v[38:41], v[160:163], v[218:221], v[38:41]
	v_mfma_f32_16x16x32_bf16 v[30:33], v[186:189], v[218:221], v[30:33]
	v_mfma_f32_16x16x32_bf16 v[22:25], v[160:163], v[226:229], v[22:25]
	v_mfma_f32_16x16x32_bf16 v[14:17], v[186:189], v[226:229], v[14:17]
	v_mfma_f32_16x16x32_bf16 v[6:9], v[160:163], v[234:237], v[6:9]
	v_mfma_f32_16x16x32_bf16 v[2:5], v[186:189], v[234:237], v[2:5]
	s_setprio 0
	s_add_i32 s84, s84, 2
	s_add_u32 s64, s64, 0x100
	s_addc_u32 s65, s65, 0
	s_add_u32 s82, s82, 0x100
	s_addc_u32 s83, s83, 0
	s_barrier
	s_cmpk_gt_u32 s84, 0x7d
	s_cbranch_scc0 .LBB0_1112
	s_and_b64 vcc, exec, s[12:13]
	s_cbranch_vccz .LBB0_1115
	s_barrier

.LBB0_1138:
	s_add_u32 s46, s62, 0xffe00080
	s_addc_u32 s47, s63, -1
	s_add_i32 s48, 0, 0x10000
	s_cmpk_eq_i32 s82, 0x7c
	s_cselect_b32 s65, s17, s47
	s_cselect_b32 s64, s78, s46
	s_cselect_b32 s61, s13, s81
	s_cselect_b32 s60, s79, s80
	s_add_i32 s49, 0, 0x14000
	v_add_u32_e32 v142, s48, v186
	v_add_u32_e32 v164, s49, v186
	ds_read_b128 v[130:133], v142
	ds_read_b128 v[134:137], v142 offset:1024
	ds_read_b128 v[138:141], v142 offset:2048
	ds_read_b128 v[142:145], v142 offset:3072
	ds_read_b128 v[146:149], v164
	ds_read_b128 v[160:163], v164 offset:1024
	ds_read_b128 v[178:181], v164 offset:2048
	ds_read_b128 v[182:185], v164 offset:3072
	v_lshl_add_u64 v[164:165], s[62:63], 0, v[156:157]
	s_add_i32 m0, s71, 0xc000
	ds_read_b128 v[206:209], v188
	ds_read_b128 v[210:213], v188 offset:1024
	ds_read_b128 v[214:217], v188 offset:2048
	ds_read_b128 v[218:221], v188 offset:3072
	ds_read_b128 v[222:225], v188 offset:4096
	ds_read_b128 v[226:229], v188 offset:5120
	ds_read_b128 v[230:233], v188 offset:6144
	ds_read_b128 v[234:237], v188 offset:7168
	global_load_lds_dwordx4 v[164:165], off
	v_lshl_add_u64 v[164:165], s[62:63], 0, v[158:159]
	s_add_i32 m0, s71, 0xe000
	s_nop 0
	global_load_lds_dwordx4 v[164:165], off
	s_waitcnt vmcnt(8)
	s_waitcnt lgkmcnt(0)
	s_setprio 1
	s_waitcnt lgkmcnt(0)
	v_mfma_f32_16x16x32_bf16 v[126:129], v[130:133], v[206:209], v[126:129]
	v_mfma_f32_16x16x32_bf16 v[122:125], v[138:141], v[206:209], v[122:125]
	v_mfma_f32_16x16x32_bf16 v[118:121], v[130:133], v[214:217], v[118:121]
	v_mfma_f32_16x16x32_bf16 v[110:113], v[138:141], v[214:217], v[110:113]
	s_barrier
	v_mfma_f32_16x16x32_bf16 v[94:97], v[130:133], v[222:225], v[94:97]
	v_mfma_f32_16x16x32_bf16 v[90:93], v[138:141], v[222:225], v[90:93]
	v_mfma_f32_16x16x32_bf16 v[82:85], v[130:133], v[230:233], v[82:85]
	v_mfma_f32_16x16x32_bf16 v[74:77], v[138:141], v[230:233], v[74:77]
	v_mfma_f32_16x16x32_bf16 v[126:129], v[134:137], v[210:213], v[126:129]
	v_mfma_f32_16x16x32_bf16 v[122:125], v[142:145], v[210:213], v[122:125]
	v_mfma_f32_16x16x32_bf16 v[118:121], v[134:137], v[218:221], v[118:121]
	v_mfma_f32_16x16x32_bf16 v[110:113], v[142:145], v[218:221], v[110:113]
	v_mfma_f32_16x16x32_bf16 v[94:97], v[134:137], v[226:229], v[94:97]
	v_mfma_f32_16x16x32_bf16 v[90:93], v[142:145], v[226:229], v[90:93]
	v_mfma_f32_16x16x32_bf16 v[82:85], v[134:137], v[234:237], v[82:85]
	v_mfma_f32_16x16x32_bf16 v[74:77], v[142:145], v[234:237], v[74:77]
	s_setprio 0
	s_setprio 1
	v_mfma_f32_16x16x32_bf16 v[114:117], v[146:149], v[206:209], v[114:117]
	v_mfma_f32_16x16x32_bf16 v[106:109], v[178:181], v[206:209], v[106:109]
	v_mfma_f32_16x16x32_bf16 v[102:105], v[146:149], v[214:217], v[102:105]
	v_mfma_f32_16x16x32_bf16 v[98:101], v[178:181], v[214:217], v[98:101]
	v_mfma_f32_16x16x32_bf16 v[86:89], v[146:149], v[222:225], v[86:89]
	v_mfma_f32_16x16x32_bf16 v[78:81], v[178:181], v[222:225], v[78:81]
	v_mfma_f32_16x16x32_bf16 v[70:73], v[146:149], v[230:233], v[70:73]
	v_mfma_f32_16x16x32_bf16 v[66:69], v[178:181], v[230:233], v[66:69]
	v_mfma_f32_16x16x32_bf16 v[114:117], v[160:163], v[210:213], v[114:117]
	v_mfma_f32_16x16x32_bf16 v[106:109], v[182:185], v[210:213], v[106:109]
	v_mfma_f32_16x16x32_bf16 v[102:105], v[160:163], v[218:221], v[102:105]
	v_mfma_f32_16x16x32_bf16 v[98:101], v[182:185], v[218:221], v[98:101]
	v_mfma_f32_16x16x32_bf16 v[86:89], v[160:163], v[226:229], v[86:89]
	v_mfma_f32_16x16x32_bf16 v[78:81], v[182:185], v[226:229], v[78:81]
	v_mfma_f32_16x16x32_bf16 v[70:73], v[160:163], v[234:237], v[70:73]
	v_mfma_f32_16x16x32_bf16 v[66:69], v[182:185], v[234:237], v[66:69]
	s_setprio 0
	s_add_i32 s46, s48, s70
	v_lshl_add_u64 v[164:165], s[60:61], 0, v[166:167]
	s_mov_b32 m0, s46
	s_barrier
	ds_read_b128 v[206:209], v188 offset:16384
	ds_read_b128 v[210:213], v188 offset:17408
	ds_read_b128 v[214:217], v188 offset:18432
	ds_read_b128 v[218:221], v188 offset:19456
	ds_read_b128 v[222:225], v188 offset:20480
	ds_read_b128 v[226:229], v188 offset:21504
	ds_read_b128 v[230:233], v188 offset:22528
	ds_read_b128 v[234:237], v188 offset:23552
	global_load_lds_dwordx4 v[164:165], off
	s_add_i32 m0, s46, 0x2000
	s_add_u32 s46, s60, 0x200000
	v_lshl_add_u64 v[242:243], s[60:61], 0, v[154:155]
	s_addc_u32 s47, s61, 0
	s_add_i32 s48, s49, s70
	global_load_lds_dwordx4 v[242:243], off
	v_lshl_add_u64 v[244:245], s[46:47], 0, v[166:167]
	s_mov_b32 m0, s48
	v_lshl_add_u64 v[246:247], s[64:65], 0, v[152:153]
	global_load_lds_dwordx4 v[244:245], off
	v_lshl_add_u64 v[244:245], s[46:47], 0, v[154:155]
	s_add_i32 m0, s48, 0x2000
	s_nop 0
	global_load_lds_dwordx4 v[244:245], off
	v_lshl_add_u64 v[244:245], s[64:65], 0, v[150:151]
	s_mov_b32 m0, s71
	s_nop 0
	global_load_lds_dwordx4 v[244:245], off
	s_mov_b32 m0, s72
	s_nop 0
	global_load_lds_dwordx4 v[246:247], off
	s_waitcnt vmcnt(8)
	s_waitcnt lgkmcnt(0)
	s_setprio 1
	s_waitcnt lgkmcnt(0)
	v_mfma_f32_16x16x32_bf16 v[62:65], v[130:133], v[206:209], v[62:65]
	v_mfma_f32_16x16x32_bf16 v[58:61], v[138:141], v[206:209], v[58:61]
	v_mfma_f32_16x16x32_bf16 v[50:53], v[130:133], v[214:217], v[50:53]
	v_mfma_f32_16x16x32_bf16 v[42:45], v[138:141], v[214:217], v[42:45]
	s_barrier
	v_mfma_f32_16x16x32_bf16 v[34:37], v[130:133], v[222:225], v[34:37]
	v_mfma_f32_16x16x32_bf16 v[26:29], v[138:141], v[222:225], v[26:29]
	v_mfma_f32_16x16x32_bf16 v[18:21], v[130:133], v[230:233], v[18:21]
	v_mfma_f32_16x16x32_bf16 v[10:13], v[138:141], v[230:233], v[10:13]
	v_mfma_f32_16x16x32_bf16 v[62:65], v[134:137], v[210:213], v[62:65]
	v_mfma_f32_16x16x32_bf16 v[58:61], v[142:145], v[210:213], v[58:61]
	v_mfma_f32_16x16x32_bf16 v[50:53], v[134:137], v[218:221], v[50:53]
	v_mfma_f32_16x16x32_bf16 v[42:45], v[142:145], v[218:221], v[42:45]
	v_mfma_f32_16x16x32_bf16 v[34:37], v[134:137], v[226:229], v[34:37]
	v_mfma_f32_16x16x32_bf16 v[26:29], v[142:145], v[226:229], v[26:29]
	v_mfma_f32_16x16x32_bf16 v[18:21], v[134:137], v[234:237], v[18:21]
	v_mfma_f32_16x16x32_bf16 v[10:13], v[142:145], v[234:237], v[10:13]
	s_setprio 0
	s_setprio 1
	v_mfma_f32_16x16x32_bf16 v[54:57], v[146:149], v[206:209], v[54:57]
	v_mfma_f32_16x16x32_bf16 v[46:49], v[178:181], v[206:209], v[46:49]
	v_mfma_f32_16x16x32_bf16 v[38:41], v[146:149], v[214:217], v[38:41]
	v_mfma_f32_16x16x32_bf16 v[30:33], v[178:181], v[214:217], v[30:33]
	v_mfma_f32_16x16x32_bf16 v[22:25], v[146:149], v[222:225], v[22:25]
	v_mfma_f32_16x16x32_bf16 v[14:17], v[178:181], v[222:225], v[14:17]
	v_mfma_f32_16x16x32_bf16 v[6:9], v[146:149], v[230:233], v[6:9]
	v_mfma_f32_16x16x32_bf16 v[2:5], v[178:181], v[230:233], v[2:5]
	v_mfma_f32_16x16x32_bf16 v[54:57], v[160:163], v[210:213], v[54:57]
	v_mfma_f32_16x16x32_bf16 v[46:49], v[182:185], v[210:213], v[46:49]
	v_mfma_f32_16x16x32_bf16 v[38:41], v[160:163], v[218:221], v[38:41]
	v_mfma_f32_16x16x32_bf16 v[30:33], v[182:185], v[218:221], v[30:33]
	v_mfma_f32_16x16x32_bf16 v[22:25], v[160:163], v[226:229], v[22:25]
	v_mfma_f32_16x16x32_bf16 v[14:17], v[182:185], v[226:229], v[14:17]
	v_mfma_f32_16x16x32_bf16 v[6:9], v[160:163], v[234:237], v[6:9]
	v_mfma_f32_16x16x32_bf16 v[2:5], v[182:185], v[234:237], v[2:5]
	s_setprio 0
	s_add_i32 s48, 0, 0x18000
	s_add_i32 s49, 0, 0x1c000
	v_add_u32_e32 v142, s48, v186
	v_add_u32_e32 v182, s49, v186
	s_barrier
	ds_read_b128 v[130:133], v142
	ds_read_b128 v[134:137], v142 offset:1024
	ds_read_b128 v[138:141], v142 offset:2048
	ds_read_b128 v[142:145], v142 offset:3072
	ds_read_b128 v[146:149], v182
	ds_read_b128 v[160:163], v182 offset:1024
	ds_read_b128 v[178:181], v182 offset:2048
	ds_read_b128 v[182:185], v182 offset:3072
	s_add_u32 s46, s64, 0x200000
	s_addc_u32 s47, s65, 0
	s_mov_b32 m0, s73
	v_lshl_add_u64 v[248:249], s[46:47], 0, v[150:151]
	ds_read_b128 v[206:209], v188 offset:32768
	ds_read_b128 v[210:213], v188 offset:33792
	ds_read_b128 v[214:217], v188 offset:34816
	ds_read_b128 v[218:221], v188 offset:35840
	ds_read_b128 v[222:225], v188 offset:36864
	ds_read_b128 v[226:229], v188 offset:37888
	ds_read_b128 v[230:233], v188 offset:38912
	ds_read_b128 v[234:237], v188 offset:39936
	global_load_lds_dwordx4 v[248:249], off
	v_lshl_add_u64 v[248:249], s[46:47], 0, v[152:153]
	s_mov_b32 m0, s74
	s_nop 0
	global_load_lds_dwordx4 v[248:249], off
	s_waitcnt vmcnt(8)
	s_waitcnt lgkmcnt(0)
	s_setprio 1
	s_waitcnt lgkmcnt(0)
	v_mfma_f32_16x16x32_bf16 v[126:129], v[130:133], v[206:209], v[126:129]
	v_mfma_f32_16x16x32_bf16 v[122:125], v[138:141], v[206:209], v[122:125]
	v_mfma_f32_16x16x32_bf16 v[118:121], v[130:133], v[214:217], v[118:121]
	v_mfma_f32_16x16x32_bf16 v[110:113], v[138:141], v[214:217], v[110:113]
	s_barrier
	v_mfma_f32_16x16x32_bf16 v[94:97], v[130:133], v[222:225], v[94:97]
	v_mfma_f32_16x16x32_bf16 v[90:93], v[138:141], v[222:225], v[90:93]
	v_mfma_f32_16x16x32_bf16 v[82:85], v[130:133], v[230:233], v[82:85]
	v_mfma_f32_16x16x32_bf16 v[74:77], v[138:141], v[230:233], v[74:77]
	v_mfma_f32_16x16x32_bf16 v[126:129], v[134:137], v[210:213], v[126:129]
	v_mfma_f32_16x16x32_bf16 v[122:125], v[142:145], v[210:213], v[122:125]
	v_mfma_f32_16x16x32_bf16 v[118:121], v[134:137], v[218:221], v[118:121]
	v_mfma_f32_16x16x32_bf16 v[110:113], v[142:145], v[218:221], v[110:113]
	v_mfma_f32_16x16x32_bf16 v[94:97], v[134:137], v[226:229], v[94:97]
	v_mfma_f32_16x16x32_bf16 v[90:93], v[142:145], v[226:229], v[90:93]
	v_mfma_f32_16x16x32_bf16 v[82:85], v[134:137], v[234:237], v[82:85]
	v_mfma_f32_16x16x32_bf16 v[74:77], v[142:145], v[234:237], v[74:77]
	s_setprio 0
	s_setprio 1
	v_mfma_f32_16x16x32_bf16 v[114:117], v[146:149], v[206:209], v[114:117]
	v_mfma_f32_16x16x32_bf16 v[106:109], v[178:181], v[206:209], v[106:109]
	v_mfma_f32_16x16x32_bf16 v[102:105], v[146:149], v[214:217], v[102:105]
	v_mfma_f32_16x16x32_bf16 v[98:101], v[178:181], v[214:217], v[98:101]
	v_mfma_f32_16x16x32_bf16 v[86:89], v[146:149], v[222:225], v[86:89]
	v_mfma_f32_16x16x32_bf16 v[78:81], v[178:181], v[222:225], v[78:81]
	v_mfma_f32_16x16x32_bf16 v[70:73], v[146:149], v[230:233], v[70:73]
	v_mfma_f32_16x16x32_bf16 v[66:69], v[178:181], v[230:233], v[66:69]
	v_mfma_f32_16x16x32_bf16 v[114:117], v[160:163], v[210:213], v[114:117]
	v_mfma_f32_16x16x32_bf16 v[106:109], v[182:185], v[210:213], v[106:109]
	v_mfma_f32_16x16x32_bf16 v[102:105], v[160:163], v[218:221], v[102:105]
	v_mfma_f32_16x16x32_bf16 v[98:101], v[182:185], v[218:221], v[98:101]
	v_mfma_f32_16x16x32_bf16 v[86:89], v[160:163], v[226:229], v[86:89]
	v_mfma_f32_16x16x32_bf16 v[78:81], v[182:185], v[226:229], v[78:81]
	v_mfma_f32_16x16x32_bf16 v[70:73], v[160:163], v[234:237], v[70:73]
	v_mfma_f32_16x16x32_bf16 v[66:69], v[182:185], v[234:237], v[66:69]
	s_setprio 0
	s_add_i32 s46, s48, s70
	v_lshl_add_u64 v[164:165], v[164:165], 0, s[42:43]
	s_mov_b32 m0, s46
	s_barrier
	ds_read_b128 v[206:209], v188 offset:49152
	ds_read_b128 v[210:213], v188 offset:50176
	ds_read_b128 v[214:217], v188 offset:51200
	ds_read_b128 v[218:221], v188 offset:52224
	ds_read_b128 v[222:225], v188 offset:53248
	ds_read_b128 v[226:229], v188 offset:54272
	ds_read_b128 v[230:233], v188 offset:55296
	ds_read_b128 v[234:237], v188 offset:56320
	global_load_lds_dwordx4 v[164:165], off
	s_add_i32 m0, s46, 0x2000
	s_add_u32 s46, s60, 0x200080
	v_lshl_add_u64 v[164:165], v[242:243], 0, s[42:43]
	s_addc_u32 s47, s61, 0
	s_add_i32 s48, s49, s70
	global_load_lds_dwordx4 v[164:165], off
	v_lshl_add_u64 v[164:165], s[46:47], 0, v[166:167]
	s_mov_b32 m0, s48
	s_nop 0
	global_load_lds_dwordx4 v[164:165], off
	v_lshl_add_u64 v[164:165], s[46:47], 0, v[154:155]
	s_add_i32 m0, s48, 0x2000
	s_nop 0
	global_load_lds_dwordx4 v[164:165], off
	v_lshl_add_u64 v[164:165], v[244:245], 0, s[42:43]
	s_mov_b32 m0, s75
	s_nop 0
	global_load_lds_dwordx4 v[164:165], off
	v_lshl_add_u64 v[164:165], v[246:247], 0, s[42:43]
	s_mov_b32 m0, s76
	s_nop 0
	global_load_lds_dwordx4 v[164:165], off
	s_waitcnt vmcnt(8)
	s_waitcnt lgkmcnt(0)
	s_setprio 1
	s_waitcnt lgkmcnt(0)
	v_mfma_f32_16x16x32_bf16 v[62:65], v[130:133], v[206:209], v[62:65]
	v_mfma_f32_16x16x32_bf16 v[58:61], v[138:141], v[206:209], v[58:61]
	v_mfma_f32_16x16x32_bf16 v[50:53], v[130:133], v[214:217], v[50:53]
	v_mfma_f32_16x16x32_bf16 v[42:45], v[138:141], v[214:217], v[42:45]
	s_barrier
	v_mfma_f32_16x16x32_bf16 v[34:37], v[130:133], v[222:225], v[34:37]
	v_mfma_f32_16x16x32_bf16 v[26:29], v[138:141], v[222:225], v[26:29]
	v_mfma_f32_16x16x32_bf16 v[18:21], v[130:133], v[230:233], v[18:21]
	v_mfma_f32_16x16x32_bf16 v[10:13], v[138:141], v[230:233], v[10:13]
	v_mfma_f32_16x16x32_bf16 v[62:65], v[134:137], v[210:213], v[62:65]
	v_mfma_f32_16x16x32_bf16 v[58:61], v[142:145], v[210:213], v[58:61]
	v_mfma_f32_16x16x32_bf16 v[50:53], v[134:137], v[218:221], v[50:53]
	v_mfma_f32_16x16x32_bf16 v[42:45], v[142:145], v[218:221], v[42:45]
	v_mfma_f32_16x16x32_bf16 v[34:37], v[134:137], v[226:229], v[34:37]
	v_mfma_f32_16x16x32_bf16 v[26:29], v[142:145], v[226:229], v[26:29]
	v_mfma_f32_16x16x32_bf16 v[18:21], v[134:137], v[234:237], v[18:21]
	v_mfma_f32_16x16x32_bf16 v[10:13], v[142:145], v[234:237], v[10:13]
	s_setprio 0
	s_setprio 1
	v_mfma_f32_16x16x32_bf16 v[54:57], v[146:149], v[206:209], v[54:57]
	v_mfma_f32_16x16x32_bf16 v[46:49], v[178:181], v[206:209], v[46:49]
	v_mfma_f32_16x16x32_bf16 v[38:41], v[146:149], v[214:217], v[38:41]
	v_mfma_f32_16x16x32_bf16 v[30:33], v[178:181], v[214:217], v[30:33]
	v_mfma_f32_16x16x32_bf16 v[22:25], v[146:149], v[222:225], v[22:25]
	v_mfma_f32_16x16x32_bf16 v[14:17], v[178:181], v[222:225], v[14:17]
	v_mfma_f32_16x16x32_bf16 v[6:9], v[146:149], v[230:233], v[6:9]
	v_mfma_f32_16x16x32_bf16 v[2:5], v[178:181], v[230:233], v[2:5]
	v_mfma_f32_16x16x32_bf16 v[54:57], v[160:163], v[210:213], v[54:57]
	v_mfma_f32_16x16x32_bf16 v[46:49], v[182:185], v[210:213], v[46:49]
	v_mfma_f32_16x16x32_bf16 v[38:41], v[160:163], v[218:221], v[38:41]
	v_mfma_f32_16x16x32_bf16 v[30:33], v[182:185], v[218:221], v[30:33]
	v_mfma_f32_16x16x32_bf16 v[22:25], v[160:163], v[226:229], v[22:25]
	v_mfma_f32_16x16x32_bf16 v[14:17], v[182:185], v[226:229], v[14:17]
	v_mfma_f32_16x16x32_bf16 v[6:9], v[160:163], v[234:237], v[6:9]
	v_mfma_f32_16x16x32_bf16 v[2:5], v[182:185], v[234:237], v[2:5]
	s_setprio 0
	s_add_i32 s82, s82, 2
	s_add_u32 s62, s62, 0x100
	s_addc_u32 s63, s63, 0
	s_add_u32 s80, s80, 0x100
	s_addc_u32 s81, s81, 0
	s_barrier
	s_cmpk_gt_u32 s82, 0x7d
	s_cbranch_scc0 .LBB0_1138
	s_and_b64 vcc, exec, s[10:11]
	s_cbranch_vccz .LBB0_1141
	s_barrier
